# P1: A-fragment VGPR tuples shifted by 2 registers (src1 starts at bank 0, src0 and C at bank 2)
# speedup vs baseline: 1.0098x; 1.0098x over previous
; #define PG8_LAS __attribute__((address_space(3)))
; #define PG8_STAGE(bufoff, gbase, voff) do { _Pragma("unroll") for (int _i = 0; _i < 2; ++_i) \
;         __builtin_amdgcn_global_load_lds((const unsigned*)((const char*)(gbase) + (voff)[_i]), (PG8_LAS unsigned*)(lds + (bufoff) + ldsw + _i * 8192), 16, 0, 0); } while (0)
; #define PG8_LDA(dst, b, h) do { _Pragma("unroll") for (int m = 0; m < 4; ++m) _Pragma("unroll") for (int k = 0; k < 2; ++k) dst[m][k] = *(const PG8_LAS bf16x8*)(lds + PG8_SA(b, h) + aoff + m * 2048 + k * 1024); } while (0)
; template <class Epi, class Sched, bool ALIGN_EPI = false, bool SP2 = false, bool RS = false, bool BPRE = false>
; __device__ __forceinline__ void gemm_phase(PG8_LAS unsigned char* lds, const Gemm g, const Sched& S, const Epi& E, const float* rs_ss = nullptr, PG8_LAS float* rs_tab = nullptr) {
;     ...
;         const bool has_next = S.next(ui + 1, nxt);
;         const char* nA = has_next ? (const char*)g.A + (size_t)nxt.pm * tstep : cA; const char* nB = has_next ? (const char*)g.Bt + (size_t)nxt.pn * tstep : cB;
;         for (int t = 0; t < nt; t += 2) {
;             const bool last = (t == nt - 2);
;             if constexpr (RS) { if (t == 16 || t == 32) { const PG8_LAS float* tp = rs_tab + (ui & 1) * 768 + (t == 32 ? 256 : 0);
;                 _Pragma("unroll") for (int a = 0; a < 2; ++a) _Pragma("unroll") for (int m = 0; m < 4; ++m) { const float f = tp[a * HALF + wr * 64 + m * 16 + fr];
;                     _Pragma("unroll") for (int b = 0; b < 2; ++b) _Pragma("unroll") for (int n = 0; n < 2; ++n) acc[a][b][m][n] = acc[a][b][m][n] * f; } } }
;             const char* a1 = cA + (size_t)(t + 1) * kstep;
;             const char* a2 = last ? nA : cA + (size_t)(t + 2) * kstep; const char* b2 = last ? nB : cB + (size_t)(t + 2) * kstep;
;             const char* a3 = a2 + kstep; const char* b3 = b2 + kstep;
;             if (last && has_next) S.a_ready(nxt);
;             if constexpr (SP2) {
;             PG8_LDB(B0, 0, 0); PG8_LDB(B1, 0, 1); PG8_SCHED; PG8_LDA(At, 0, 0); PG8_STAGE(PG8_SA(1, 1), a1 + hstep, voffA);
;             PG8_WAIT_V(8); PG8_WAIT_L(0); PG8_BAR; PG8_MMA(0, 0, At, B0); PG8_MMA(0, 1, At, B1); PG8_BAR; PG8_SCHED;
;             PG8_LDA(At, 0, 1); PG8_STAGE(PG8_SB(0, 0), b2, voffB); PG8_STAGE(PG8_SB(0, 1), b2 + hstep, voffB); PG8_STAGE(PG8_SA(0, 0), a2, voffA);
.LBB0_195:
	s_ashr_i32 s19, s18, 31
	s_lshl_b64 s[20:21], s[18:19], 20
	s_add_u32 s20, s30, s20
	s_addc_u32 s21, s31, s21
	s_and_b64 s[44:45], s[6:7], exec
	s_cselect_b32 s5, s21, s57
	s_cselect_b32 s19, s20, s56
	s_ashr_i32 s17, s16, 31
	s_lshl_b64 s[44:45], s[16:17], 20
	s_add_u32 s44, s24, s44
	s_addc_u32 s45, s25, s45
	s_and_b64 s[60:61], s[6:7], exec
	s_cselect_b32 s17, s45, s59
	s_cselect_b32 s47, s44, s58
	s_add_u32 s56, s56, 0x84000
	s_addc_u32 s57, s57, 0
	s_add_u32 s87, s58, 0x8000
	s_addc_u32 s88, s59, 0
	s_mov_b32 s89, -2
	s_waitcnt lgkmcnt(0)
	ds_read_b128 v[130:133], v161
	ds_read_b128 v[134:137], v161 offset:1024
	ds_read_b128 v[152:155], v161 offset:2048
	ds_read_b128 v[156:159], v161 offset:3072
	ds_read_b128 v[166:169], v162
	ds_read_b128 v[170:173], v162 offset:1024
	ds_read_b128 v[174:177], v162 offset:2048
	ds_read_b128 v[182:185], v162 offset:3072
	s_add_u32 s58, s56, 0xfff84000
	s_addc_u32 s59, s57, -1
	s_cmp_eq_u32 s89, 28
	s_cselect_b32 s70, s19, s58
	s_cselect_b32 s71, s5, s59
	s_cselect_b32 s60, s47, s87
	s_cselect_b32 s61, s17, s88
	s_add_u32 s58, s70, 0x4000
	s_addc_u32 s59, s71, 0
	v_lshl_add_u64 v[178:179], s[56:57], 0, v[138:139]
	s_add_i32 m0, s72, 0xc000
	ds_read_b128 v[188:191], v163
	ds_read_b128 v[192:195], v163 offset:1024
	ds_read_b128 v[196:199], v163 offset:2048
	ds_read_b128 v[200:203], v163 offset:3072
	ds_read_b128 v[204:207], v163 offset:4096
	ds_read_b128 v[208:211], v163 offset:5120
	ds_read_b128 v[212:215], v163 offset:6144
	ds_read_b128 v[216:219], v163 offset:7168
	global_load_lds_dwordx4 v[178:179], off
	v_lshl_add_u64 v[178:179], s[56:57], 0, v[146:147]
	s_add_i32 m0, s72, 0xe000
	s_nop 0
	global_load_lds_dwordx4 v[178:179], off
	s_waitcnt vmcnt(8)
	s_waitcnt lgkmcnt(0)
	s_barrier
	s_setprio 1
	s_waitcnt lgkmcnt(0)
	v_mfma_f32_16x16x32_bf16 v[126:129], v[130:133], v[188:191], 0
	v_mfma_f32_16x16x32_bf16 v[126:129], v[134:137], v[192:195], v[126:129]
	v_mfma_f32_16x16x32_bf16 v[122:125], v[156:159], v[192:195], 0
	v_mfma_f32_16x16x32_bf16 v[122:125], v[152:155], v[188:191], v[122:125]
	v_mfma_f32_16x16x32_bf16 v[106:109], v[152:155], v[196:199], 0
	v_mfma_f32_16x16x32_bf16 v[106:109], v[156:159], v[200:203], v[106:109]
	v_mfma_f32_16x16x32_bf16 v[110:113], v[134:137], v[200:203], 0
	v_mfma_f32_16x16x32_bf16 v[110:113], v[130:133], v[196:199], v[110:113]
	v_mfma_f32_16x16x32_bf16 v[94:97], v[130:133], v[204:207], 0
	v_mfma_f32_16x16x32_bf16 v[94:97], v[134:137], v[208:211], v[94:97]
	v_mfma_f32_16x16x32_bf16 v[90:93], v[156:159], v[208:211], 0
	v_mfma_f32_16x16x32_bf16 v[90:93], v[152:155], v[204:207], v[90:93]
	v_mfma_f32_16x16x32_bf16 v[74:77], v[152:155], v[212:215], 0
	v_mfma_f32_16x16x32_bf16 v[74:77], v[156:159], v[216:219], v[74:77]
	v_mfma_f32_16x16x32_bf16 v[78:81], v[134:137], v[216:219], 0
	v_mfma_f32_16x16x32_bf16 v[78:81], v[130:133], v[212:215], v[78:81]
	s_setprio 0
	s_setprio 1
	v_mfma_f32_16x16x32_bf16 v[70:73], v[166:169], v[212:215], 0
	v_mfma_f32_16x16x32_bf16 v[70:73], v[170:173], v[216:219], v[70:73]
	v_mfma_f32_16x16x32_bf16 v[66:69], v[182:185], v[216:219], 0
	v_mfma_f32_16x16x32_bf16 v[66:69], v[174:177], v[212:215], v[66:69]
	v_mfma_f32_16x16x32_bf16 v[82:85], v[174:177], v[204:207], 0
	v_mfma_f32_16x16x32_bf16 v[82:85], v[182:185], v[208:211], v[82:85]
	v_mfma_f32_16x16x32_bf16 v[86:89], v[170:173], v[208:211], 0
	v_mfma_f32_16x16x32_bf16 v[86:89], v[166:169], v[204:207], v[86:89]
	v_mfma_f32_16x16x32_bf16 v[102:105], v[166:169], v[196:199], 0
	v_mfma_f32_16x16x32_bf16 v[102:105], v[170:173], v[200:203], v[102:105]
	v_mfma_f32_16x16x32_bf16 v[98:101], v[182:185], v[200:203], 0
	v_mfma_f32_16x16x32_bf16 v[98:101], v[174:177], v[196:199], v[98:101]
	v_mfma_f32_16x16x32_bf16 v[114:117], v[174:177], v[188:191], 0
	v_mfma_f32_16x16x32_bf16 v[114:117], v[182:185], v[192:195], v[114:117]
	v_mfma_f32_16x16x32_bf16 v[118:121], v[170:173], v[192:195], 0
	v_mfma_f32_16x16x32_bf16 v[118:121], v[166:169], v[188:191], v[118:121]
	s_setprio 0
	s_barrier
	s_add_i32 s90, s83, s15
	v_lshl_add_u64 v[178:179], s[60:61], 0, v[138:139]
	s_mov_b32 m0, s90
	ds_read_b128 v[188:191], v163 offset:16384
	ds_read_b128 v[192:195], v163 offset:17408
	ds_read_b128 v[196:199], v163 offset:18432
	ds_read_b128 v[200:203], v163 offset:19456
	ds_read_b128 v[204:207], v163 offset:20480
	ds_read_b128 v[208:211], v163 offset:21504
	ds_read_b128 v[212:215], v163 offset:22528
	ds_read_b128 v[216:219], v163 offset:23552
	global_load_lds_dwordx4 v[178:179], off
	s_add_i32 m0, s90, 0x2000
	s_add_u32 s90, s60, 0x80000
	v_lshl_add_u64 v[178:179], s[60:61], 0, v[140:141]
	s_addc_u32 s91, s61, 0
	s_add_i32 s92, s86, s15
	global_load_lds_dwordx4 v[178:179], off
	v_lshl_add_u64 v[178:179], s[90:91], 0, v[138:139]
	s_mov_b32 m0, s92
	s_nop 0
	global_load_lds_dwordx4 v[178:179], off
	v_lshl_add_u64 v[178:179], s[90:91], 0, v[140:141]
	s_add_i32 m0, s92, 0x2000
	s_nop 0
	global_load_lds_dwordx4 v[178:179], off
	v_lshl_add_u64 v[178:179], s[70:71], 0, v[138:139]
	s_mov_b32 m0, s72
	s_nop 0
	global_load_lds_dwordx4 v[178:179], off
	v_lshl_add_u64 v[178:179], s[70:71], 0, v[140:141]
	s_mov_b32 m0, s73
	s_nop 0
	global_load_lds_dwordx4 v[178:179], off
	s_waitcnt vmcnt(8)
	s_waitcnt lgkmcnt(0)
	s_barrier
; #define PG8_STAGE(bufoff, gbase, voff) do { _Pragma("unroll") for (int _i = 0; _i < 2; ++_i) \
;         __builtin_amdgcn_global_load_lds((const unsigned*)((const char*)(gbase) + (voff)[_i]), (PG8_LAS unsigned*)(lds + (bufoff) + ldsw + _i * 8192), 16, 0, 0); } while (0)
; #define PG8_LDA(dst, b, h) do { _Pragma("unroll") for (int m = 0; m < 4; ++m) _Pragma("unroll") for (int k = 0; k < 2; ++k) dst[m][k] = *(const PG8_LAS bf16x8*)(lds + PG8_SA(b, h) + aoff + m * 2048 + k * 1024); } while (0)
; #define PG8_LDB(dst, b, h) do { _Pragma("unroll") for (int n = 0; n < 2; ++n) _Pragma("unroll") for (int k = 0; k < 2; ++k) dst[n][k] = *(const PG8_LAS bf16x8*)(lds + PG8_SB(b, h) + boff + n * 2048 + k * 1024); } while (0)
; #define PG8_WAIT_V(n) asm volatile("s_waitcnt vmcnt(" #n ")" ::: "memory")
; #define PG8_WAIT_L(n) asm volatile("s_waitcnt lgkmcnt(" #n ")" ::: "memory")
; #define PG8_BAR __builtin_amdgcn_s_barrier()
; #define PG8_SCHED __builtin_amdgcn_sched_barrier(0)
; template <class Epi, class Sched, bool ALIGN_EPI = false, bool SP2 = false, bool RS = false, bool BPRE = false>
; __device__ __forceinline__ void gemm_phase(PG8_LAS unsigned char* lds, const Gemm g, const Sched& S, const Epi& E, const float* rs_ss = nullptr, PG8_LAS float* rs_tab = nullptr) {
;     ...
;             PG8_LDB(B0, 0, 0); PG8_LDB(B1, 0, 1); PG8_SCHED; PG8_LDA(At, 0, 0); PG8_STAGE(PG8_SA(1, 1), a1 + hstep, voffA);
;             PG8_WAIT_V(8); PG8_WAIT_L(0); PG8_BAR; PG8_MMA(0, 0, At, B0); PG8_MMA(0, 1, At, B1); PG8_BAR; PG8_SCHED;
;             PG8_LDA(At, 0, 1); PG8_STAGE(PG8_SB(0, 0), b2, voffB); PG8_STAGE(PG8_SB(0, 1), b2 + hstep, voffB); PG8_STAGE(PG8_SA(0, 0), a2, voffA);
;             PG8_WAIT_V(8); PG8_WAIT_L(0); PG8_BAR; PG8_MMA(1, 0, At, B0); PG8_MMA(1, 1, At, B1); PG8_BAR; PG8_SCHED;
;             PG8_LDB(B0, 1, 0); PG8_LDB(B1, 1, 1); PG8_SCHED; PG8_LDA(At, 1, 0); PG8_STAGE(PG8_SA(0, 1), a2 + hstep, voffA);
;             PG8_WAIT_V(8); PG8_WAIT_L(0); PG8_BAR; PG8_MMA(0, 0, At, B0); PG8_MMA(0, 1, At, B1); PG8_BAR; PG8_SCHED;
;             PG8_LDA(At, 1, 1); PG8_STAGE(PG8_SB(1, 0), b3, voffB); PG8_STAGE(PG8_SB(1, 1), b3 + hstep, voffB); PG8_STAGE(PG8_SA(1, 0), a3, voffA);
;             PG8_WAIT_V(8); PG8_WAIT_L(0); PG8_BAR; PG8_MMA(1, 0, At, B0); PG8_MMA(1, 1, At, B1); PG8_BAR; PG8_SCHED;
	s_setprio 1
	s_waitcnt lgkmcnt(0)
	v_mfma_f32_16x16x32_bf16 v[62:65], v[130:133], v[188:191], 0
	v_mfma_f32_16x16x32_bf16 v[62:65], v[134:137], v[192:195], v[62:65]
	v_mfma_f32_16x16x32_bf16 v[58:61], v[156:159], v[192:195], 0
	v_mfma_f32_16x16x32_bf16 v[58:61], v[152:155], v[188:191], v[58:61]
	v_mfma_f32_16x16x32_bf16 v[42:45], v[152:155], v[196:199], 0
	v_mfma_f32_16x16x32_bf16 v[42:45], v[156:159], v[200:203], v[42:45]
	v_mfma_f32_16x16x32_bf16 v[46:49], v[134:137], v[200:203], 0
	v_mfma_f32_16x16x32_bf16 v[46:49], v[130:133], v[196:199], v[46:49]
	v_mfma_f32_16x16x32_bf16 v[30:33], v[130:133], v[204:207], 0
	v_mfma_f32_16x16x32_bf16 v[30:33], v[134:137], v[208:211], v[30:33]
	v_mfma_f32_16x16x32_bf16 v[26:29], v[156:159], v[208:211], 0
	v_mfma_f32_16x16x32_bf16 v[26:29], v[152:155], v[204:207], v[26:29]
	v_mfma_f32_16x16x32_bf16 v[10:13], v[152:155], v[212:215], 0
	v_mfma_f32_16x16x32_bf16 v[10:13], v[156:159], v[216:219], v[10:13]
	v_mfma_f32_16x16x32_bf16 v[14:17], v[134:137], v[216:219], 0
	v_mfma_f32_16x16x32_bf16 v[14:17], v[130:133], v[212:215], v[14:17]
	s_setprio 0
	s_setprio 1
	v_mfma_f32_16x16x32_bf16 v[6:9], v[166:169], v[212:215], 0
	v_mfma_f32_16x16x32_bf16 v[6:9], v[170:173], v[216:219], v[6:9]
	v_mfma_f32_16x16x32_bf16 v[2:5], v[182:185], v[216:219], 0
	v_mfma_f32_16x16x32_bf16 v[2:5], v[174:177], v[212:215], v[2:5]
	v_mfma_f32_16x16x32_bf16 v[18:21], v[174:177], v[204:207], 0
	v_mfma_f32_16x16x32_bf16 v[18:21], v[182:185], v[208:211], v[18:21]
	v_mfma_f32_16x16x32_bf16 v[22:25], v[170:173], v[208:211], 0
	v_mfma_f32_16x16x32_bf16 v[22:25], v[166:169], v[204:207], v[22:25]
	v_mfma_f32_16x16x32_bf16 v[38:41], v[166:169], v[196:199], 0
	v_mfma_f32_16x16x32_bf16 v[38:41], v[170:173], v[200:203], v[38:41]
	v_mfma_f32_16x16x32_bf16 v[34:37], v[182:185], v[200:203], 0
	v_mfma_f32_16x16x32_bf16 v[34:37], v[174:177], v[196:199], v[34:37]
	v_mfma_f32_16x16x32_bf16 v[50:53], v[174:177], v[188:191], 0
	v_mfma_f32_16x16x32_bf16 v[50:53], v[182:185], v[192:195], v[50:53]
	v_mfma_f32_16x16x32_bf16 v[54:57], v[170:173], v[192:195], 0
	v_mfma_f32_16x16x32_bf16 v[54:57], v[166:169], v[188:191], v[54:57]
	s_setprio 0
	s_barrier
	s_add_i32 s90, 0, 0x18000
	v_add_u32_e32 v143, s90, v160
	s_add_i32 s91, 0, 0x1c000
	ds_read_b128 v[130:133], v143
	ds_read_b128 v[134:137], v143 offset:1024
	ds_read_b128 v[152:155], v143 offset:2048
	ds_read_b128 v[156:159], v143 offset:3072
	v_add_u32_e32 v143, s91, v160
	ds_read_b128 v[166:169], v143
	ds_read_b128 v[170:173], v143 offset:1024
	ds_read_b128 v[174:177], v143 offset:2048
	ds_read_b128 v[182:185], v143 offset:3072
	s_add_u32 s70, s70, 0x80000
	s_addc_u32 s71, s71, 0
	s_mov_b32 m0, s74
	v_lshl_add_u64 v[178:179], s[70:71], 0, v[138:139]
	ds_read_b128 v[188:191], v163 offset:32768
	ds_read_b128 v[192:195], v163 offset:33792
	ds_read_b128 v[196:199], v163 offset:34816
	ds_read_b128 v[200:203], v163 offset:35840
	ds_read_b128 v[204:207], v163 offset:36864
	ds_read_b128 v[208:211], v163 offset:37888
	ds_read_b128 v[212:215], v163 offset:38912
	ds_read_b128 v[216:219], v163 offset:39936
	global_load_lds_dwordx4 v[178:179], off
	v_lshl_add_u64 v[178:179], s[70:71], 0, v[140:141]
	s_mov_b32 m0, s75
	s_nop 0
	global_load_lds_dwordx4 v[178:179], off
	s_waitcnt vmcnt(8)
	s_waitcnt lgkmcnt(0)
	s_barrier
	s_setprio 1
	s_waitcnt lgkmcnt(0)
	v_mfma_f32_16x16x32_bf16 v[126:129], v[130:133], v[188:191], v[126:129]
	v_mfma_f32_16x16x32_bf16 v[126:129], v[134:137], v[192:195], v[126:129]
	v_mfma_f32_16x16x32_bf16 v[122:125], v[156:159], v[192:195], v[122:125]
	v_mfma_f32_16x16x32_bf16 v[122:125], v[152:155], v[188:191], v[122:125]
	v_mfma_f32_16x16x32_bf16 v[106:109], v[152:155], v[196:199], v[106:109]
	v_mfma_f32_16x16x32_bf16 v[106:109], v[156:159], v[200:203], v[106:109]
	v_mfma_f32_16x16x32_bf16 v[110:113], v[134:137], v[200:203], v[110:113]
	v_mfma_f32_16x16x32_bf16 v[110:113], v[130:133], v[196:199], v[110:113]
	v_mfma_f32_16x16x32_bf16 v[94:97], v[130:133], v[204:207], v[94:97]
	v_mfma_f32_16x16x32_bf16 v[94:97], v[134:137], v[208:211], v[94:97]
	v_mfma_f32_16x16x32_bf16 v[90:93], v[156:159], v[208:211], v[90:93]
	v_mfma_f32_16x16x32_bf16 v[90:93], v[152:155], v[204:207], v[90:93]
	v_mfma_f32_16x16x32_bf16 v[74:77], v[152:155], v[212:215], v[74:77]
	v_mfma_f32_16x16x32_bf16 v[74:77], v[156:159], v[216:219], v[74:77]
	v_mfma_f32_16x16x32_bf16 v[78:81], v[134:137], v[216:219], v[78:81]
	v_mfma_f32_16x16x32_bf16 v[78:81], v[130:133], v[212:215], v[78:81]
	s_setprio 0
	s_setprio 1
	v_mfma_f32_16x16x32_bf16 v[70:73], v[166:169], v[212:215], v[70:73]
	v_mfma_f32_16x16x32_bf16 v[70:73], v[170:173], v[216:219], v[70:73]
	v_mfma_f32_16x16x32_bf16 v[66:69], v[182:185], v[216:219], v[66:69]
	v_mfma_f32_16x16x32_bf16 v[66:69], v[174:177], v[212:215], v[66:69]
	v_mfma_f32_16x16x32_bf16 v[82:85], v[174:177], v[204:207], v[82:85]
	v_mfma_f32_16x16x32_bf16 v[82:85], v[182:185], v[208:211], v[82:85]
	v_mfma_f32_16x16x32_bf16 v[86:89], v[170:173], v[208:211], v[86:89]
	v_mfma_f32_16x16x32_bf16 v[86:89], v[166:169], v[204:207], v[86:89]
	v_mfma_f32_16x16x32_bf16 v[102:105], v[166:169], v[196:199], v[102:105]
	v_mfma_f32_16x16x32_bf16 v[102:105], v[170:173], v[200:203], v[102:105]
	v_mfma_f32_16x16x32_bf16 v[98:101], v[182:185], v[200:203], v[98:101]
	v_mfma_f32_16x16x32_bf16 v[98:101], v[174:177], v[196:199], v[98:101]
	v_mfma_f32_16x16x32_bf16 v[114:117], v[174:177], v[188:191], v[114:117]
	v_mfma_f32_16x16x32_bf16 v[114:117], v[182:185], v[192:195], v[114:117]
	v_mfma_f32_16x16x32_bf16 v[118:121], v[170:173], v[192:195], v[118:121]
	v_mfma_f32_16x16x32_bf16 v[118:121], v[166:169], v[188:191], v[118:121]
	s_setprio 0
	s_barrier
; #define PG8_STAGE(bufoff, gbase, voff) do { _Pragma("unroll") for (int _i = 0; _i < 2; ++_i) \
;         __builtin_amdgcn_global_load_lds((const unsigned*)((const char*)(gbase) + (voff)[_i]), (PG8_LAS unsigned*)(lds + (bufoff) + ldsw + _i * 8192), 16, 0, 0); } while (0)
; #define PG8_LDA(dst, b, h) do { _Pragma("unroll") for (int m = 0; m < 4; ++m) _Pragma("unroll") for (int k = 0; k < 2; ++k) dst[m][k] = *(const PG8_LAS bf16x8*)(lds + PG8_SA(b, h) + aoff + m * 2048 + k * 1024); } while (0)
; #define PG8_LDB(dst, b, h) do { _Pragma("unroll") for (int n = 0; n < 2; ++n) _Pragma("unroll") for (int k = 0; k < 2; ++k) dst[n][k] = *(const PG8_LAS bf16x8*)(lds + PG8_SB(b, h) + boff + n * 2048 + k * 1024); } while (0)
; #define PG8_WAIT_V(n) asm volatile("s_waitcnt vmcnt(" #n ")" ::: "memory")
; #define PG8_WAIT_L(n) asm volatile("s_waitcnt lgkmcnt(" #n ")" ::: "memory")
; #define PG8_BAR __builtin_amdgcn_s_barrier()
; #define PG8_SCHED __builtin_amdgcn_sched_barrier(0)
; template <class Epi, class Sched, bool ALIGN_EPI = false, bool SP2 = false, bool RS = false, bool BPRE = false>
; __device__ __forceinline__ void gemm_phase(PG8_LAS unsigned char* lds, const Gemm g, const Sched& S, const Epi& E, const float* rs_ss = nullptr, PG8_LAS float* rs_tab = nullptr) {
;     ...
;             PG8_LDB(B0, 0, 0); PG8_LDB(B1, 0, 1); PG8_SCHED; PG8_LDA(At, 0, 0); PG8_STAGE(PG8_SA(1, 1), a1 + hstep, voffA);
;             PG8_WAIT_V(8); PG8_WAIT_L(0); PG8_BAR; PG8_MMA(0, 0, At, B0); PG8_MMA(0, 1, At, B1); PG8_BAR; PG8_SCHED;
;             PG8_LDA(At, 0, 1); PG8_STAGE(PG8_SB(0, 0), b2, voffB); PG8_STAGE(PG8_SB(0, 1), b2 + hstep, voffB); PG8_STAGE(PG8_SA(0, 0), a2, voffA);
;             PG8_WAIT_V(8); PG8_WAIT_L(0); PG8_BAR; PG8_MMA(1, 0, At, B0); PG8_MMA(1, 1, At, B1); PG8_BAR; PG8_SCHED;
;             PG8_LDB(B0, 1, 0); PG8_LDB(B1, 1, 1); PG8_SCHED; PG8_LDA(At, 1, 0); PG8_STAGE(PG8_SA(0, 1), a2 + hstep, voffA);
;             PG8_WAIT_V(8); PG8_WAIT_L(0); PG8_BAR; PG8_MMA(0, 0, At, B0); PG8_MMA(0, 1, At, B1); PG8_BAR; PG8_SCHED;
;             PG8_LDA(At, 1, 1); PG8_STAGE(PG8_SB(1, 0), b3, voffB); PG8_STAGE(PG8_SB(1, 1), b3 + hstep, voffB); PG8_STAGE(PG8_SA(1, 0), a3, voffA);
;             PG8_WAIT_V(8); PG8_WAIT_L(0); PG8_BAR; PG8_MMA(1, 0, At, B0); PG8_MMA(1, 1, At, B1); PG8_BAR; PG8_SCHED;
	s_add_u32 s70, s60, 0x4000
	s_addc_u32 s71, s61, 0
	s_add_i32 s90, s90, s15
	v_lshl_add_u64 v[178:179], s[70:71], 0, v[138:139]
	s_mov_b32 m0, s90
	ds_read_b128 v[188:191], v163 offset:49152
	ds_read_b128 v[192:195], v163 offset:50176
	ds_read_b128 v[196:199], v163 offset:51200
	ds_read_b128 v[200:203], v163 offset:52224
	ds_read_b128 v[204:207], v163 offset:53248
	ds_read_b128 v[208:211], v163 offset:54272
	ds_read_b128 v[212:215], v163 offset:55296
	ds_read_b128 v[216:219], v163 offset:56320
	global_load_lds_dwordx4 v[178:179], off
	s_add_i32 m0, s90, 0x2000
	s_add_u32 s60, s60, 0x84000
	v_lshl_add_u64 v[178:179], s[70:71], 0, v[140:141]
	s_addc_u32 s61, s61, 0
	s_add_i32 s70, s91, s15
	global_load_lds_dwordx4 v[178:179], off
	v_lshl_add_u64 v[178:179], s[60:61], 0, v[138:139]
	s_mov_b32 m0, s70
	s_nop 0
	global_load_lds_dwordx4 v[178:179], off
	v_lshl_add_u64 v[178:179], s[60:61], 0, v[140:141]
	s_add_i32 m0, s70, 0x2000
	s_nop 0
	global_load_lds_dwordx4 v[178:179], off
	v_lshl_add_u64 v[178:179], s[58:59], 0, v[138:139]
	s_mov_b32 m0, s79
	s_nop 0
	global_load_lds_dwordx4 v[178:179], off
	v_lshl_add_u64 v[178:179], s[58:59], 0, v[140:141]
	s_mov_b32 m0, s80
	s_nop 0
	global_load_lds_dwordx4 v[178:179], off
	s_waitcnt vmcnt(8)
	s_waitcnt lgkmcnt(0)
	s_barrier
	s_setprio 1
	s_waitcnt lgkmcnt(0)
	v_mfma_f32_16x16x32_bf16 v[62:65], v[130:133], v[188:191], v[62:65]
	v_mfma_f32_16x16x32_bf16 v[62:65], v[134:137], v[192:195], v[62:65]
	v_mfma_f32_16x16x32_bf16 v[58:61], v[156:159], v[192:195], v[58:61]
	v_mfma_f32_16x16x32_bf16 v[58:61], v[152:155], v[188:191], v[58:61]
	v_mfma_f32_16x16x32_bf16 v[42:45], v[152:155], v[196:199], v[42:45]
	v_mfma_f32_16x16x32_bf16 v[42:45], v[156:159], v[200:203], v[42:45]
	v_mfma_f32_16x16x32_bf16 v[46:49], v[134:137], v[200:203], v[46:49]
	v_mfma_f32_16x16x32_bf16 v[46:49], v[130:133], v[196:199], v[46:49]
	v_mfma_f32_16x16x32_bf16 v[30:33], v[130:133], v[204:207], v[30:33]
	v_mfma_f32_16x16x32_bf16 v[30:33], v[134:137], v[208:211], v[30:33]
	v_mfma_f32_16x16x32_bf16 v[26:29], v[156:159], v[208:211], v[26:29]
	v_mfma_f32_16x16x32_bf16 v[26:29], v[152:155], v[204:207], v[26:29]
	v_mfma_f32_16x16x32_bf16 v[10:13], v[152:155], v[212:215], v[10:13]
	v_mfma_f32_16x16x32_bf16 v[10:13], v[156:159], v[216:219], v[10:13]
	v_mfma_f32_16x16x32_bf16 v[14:17], v[134:137], v[216:219], v[14:17]
	v_mfma_f32_16x16x32_bf16 v[14:17], v[130:133], v[212:215], v[14:17]
	s_setprio 0
	s_setprio 1
	v_mfma_f32_16x16x32_bf16 v[6:9], v[166:169], v[212:215], v[6:9]
	v_mfma_f32_16x16x32_bf16 v[6:9], v[170:173], v[216:219], v[6:9]
	v_mfma_f32_16x16x32_bf16 v[2:5], v[182:185], v[216:219], v[2:5]
	v_mfma_f32_16x16x32_bf16 v[2:5], v[174:177], v[212:215], v[2:5]
	v_mfma_f32_16x16x32_bf16 v[18:21], v[174:177], v[204:207], v[18:21]
	v_mfma_f32_16x16x32_bf16 v[18:21], v[182:185], v[208:211], v[18:21]
	v_mfma_f32_16x16x32_bf16 v[22:25], v[170:173], v[208:211], v[22:25]
	v_mfma_f32_16x16x32_bf16 v[22:25], v[166:169], v[204:207], v[22:25]
	v_mfma_f32_16x16x32_bf16 v[38:41], v[166:169], v[196:199], v[38:41]
	v_mfma_f32_16x16x32_bf16 v[38:41], v[170:173], v[200:203], v[38:41]
	v_mfma_f32_16x16x32_bf16 v[34:37], v[182:185], v[200:203], v[34:37]
	v_mfma_f32_16x16x32_bf16 v[34:37], v[174:177], v[196:199], v[34:37]
	v_mfma_f32_16x16x32_bf16 v[50:53], v[174:177], v[188:191], v[50:53]
	v_mfma_f32_16x16x32_bf16 v[50:53], v[182:185], v[192:195], v[50:53]
	v_mfma_f32_16x16x32_bf16 v[54:57], v[170:173], v[192:195], v[54:57]
	v_mfma_f32_16x16x32_bf16 v[54:57], v[166:169], v[188:191], v[54:57]
	s_setprio 0
	s_barrier
	s_add_i32 s89, s89, 2
	s_add_u32 s56, s56, 0x8000
	s_addc_u32 s57, s57, 0
	s_add_u32 s87, s87, 0x8000
	s_addc_u32 s88, s88, 0
.LBB0_196:
	ds_read_b128 v[130:133], v161
	ds_read_b128 v[134:137], v161 offset:1024
	ds_read_b128 v[152:155], v161 offset:2048
	ds_read_b128 v[156:159], v161 offset:3072
	ds_read_b128 v[166:169], v162
	ds_read_b128 v[170:173], v162 offset:1024
	ds_read_b128 v[174:177], v162 offset:2048
	ds_read_b128 v[182:185], v162 offset:3072
	s_add_u32 s58, s56, 0xfff84000
	s_addc_u32 s59, s57, -1
	s_cmp_eq_u32 s89, 28
	s_cselect_b32 s70, s19, s58
	s_cselect_b32 s71, s5, s59
	s_cselect_b32 s60, s47, s87
	s_cselect_b32 s61, s17, s88
	s_add_u32 s58, s70, 0x4000
	s_addc_u32 s59, s71, 0
	v_lshl_add_u64 v[178:179], s[56:57], 0, v[138:139]
	s_add_i32 m0, s72, 0xc000
	ds_read_b128 v[188:191], v163
	ds_read_b128 v[192:195], v163 offset:1024
	ds_read_b128 v[196:199], v163 offset:2048
	ds_read_b128 v[200:203], v163 offset:3072
	ds_read_b128 v[204:207], v163 offset:4096
	ds_read_b128 v[208:211], v163 offset:5120
	ds_read_b128 v[212:215], v163 offset:6144
	ds_read_b128 v[216:219], v163 offset:7168
	global_load_lds_dwordx4 v[178:179], off
	v_lshl_add_u64 v[178:179], s[56:57], 0, v[146:147]
	s_add_i32 m0, s72, 0xe000
	s_nop 0
	global_load_lds_dwordx4 v[178:179], off
	s_waitcnt vmcnt(8)
	s_waitcnt lgkmcnt(0)
	s_barrier
; #define PG8_STAGE(bufoff, gbase, voff) do { _Pragma("unroll") for (int _i = 0; _i < 2; ++_i) \
;         __builtin_amdgcn_global_load_lds((const unsigned*)((const char*)(gbase) + (voff)[_i]), (PG8_LAS unsigned*)(lds + (bufoff) + ldsw + _i * 8192), 16, 0, 0); } while (0)
; #define PG8_LDA(dst, b, h) do { _Pragma("unroll") for (int m = 0; m < 4; ++m) _Pragma("unroll") for (int k = 0; k < 2; ++k) dst[m][k] = *(const PG8_LAS bf16x8*)(lds + PG8_SA(b, h) + aoff + m * 2048 + k * 1024); } while (0)
; #define PG8_LDB(dst, b, h) do { _Pragma("unroll") for (int n = 0; n < 2; ++n) _Pragma("unroll") for (int k = 0; k < 2; ++k) dst[n][k] = *(const PG8_LAS bf16x8*)(lds + PG8_SB(b, h) + boff + n * 2048 + k * 1024); } while (0)
; #define PG8_WAIT_V(n) asm volatile("s_waitcnt vmcnt(" #n ")" ::: "memory")
; #define PG8_WAIT_L(n) asm volatile("s_waitcnt lgkmcnt(" #n ")" ::: "memory")
; #define PG8_BAR __builtin_amdgcn_s_barrier()
; #define PG8_SCHED __builtin_amdgcn_sched_barrier(0)
; template <class Epi, class Sched, bool ALIGN_EPI = false, bool SP2 = false, bool RS = false, bool BPRE = false>
; __device__ __forceinline__ void gemm_phase(PG8_LAS unsigned char* lds, const Gemm g, const Sched& S, const Epi& E, const float* rs_ss = nullptr, PG8_LAS float* rs_tab = nullptr) {
;     ...
;             PG8_LDB(B0, 0, 0); PG8_LDB(B1, 0, 1); PG8_SCHED; PG8_LDA(At, 0, 0); PG8_STAGE(PG8_SA(1, 1), a1 + hstep, voffA);
;             PG8_WAIT_V(8); PG8_WAIT_L(0); PG8_BAR; PG8_MMA(0, 0, At, B0); PG8_MMA(0, 1, At, B1); PG8_BAR; PG8_SCHED;
;             PG8_LDA(At, 0, 1); PG8_STAGE(PG8_SB(0, 0), b2, voffB); PG8_STAGE(PG8_SB(0, 1), b2 + hstep, voffB); PG8_STAGE(PG8_SA(0, 0), a2, voffA);
;             PG8_WAIT_V(8); PG8_WAIT_L(0); PG8_BAR; PG8_MMA(1, 0, At, B0); PG8_MMA(1, 1, At, B1); PG8_BAR; PG8_SCHED;
;             PG8_LDB(B0, 1, 0); PG8_LDB(B1, 1, 1); PG8_SCHED; PG8_LDA(At, 1, 0); PG8_STAGE(PG8_SA(0, 1), a2 + hstep, voffA);
;             PG8_WAIT_V(8); PG8_WAIT_L(0); PG8_BAR; PG8_MMA(0, 0, At, B0); PG8_MMA(0, 1, At, B1); PG8_BAR; PG8_SCHED;
;             PG8_LDA(At, 1, 1); PG8_STAGE(PG8_SB(1, 0), b3, voffB); PG8_STAGE(PG8_SB(1, 1), b3 + hstep, voffB); PG8_STAGE(PG8_SA(1, 0), a3, voffA);
;             PG8_WAIT_V(8); PG8_WAIT_L(0); PG8_BAR; PG8_MMA(1, 0, At, B0); PG8_MMA(1, 1, At, B1); PG8_BAR; PG8_SCHED;
	s_setprio 1
	s_waitcnt lgkmcnt(0)
	v_mfma_f32_16x16x32_bf16 v[126:129], v[130:133], v[188:191], v[126:129]
	v_mfma_f32_16x16x32_bf16 v[126:129], v[134:137], v[192:195], v[126:129]
	v_mfma_f32_16x16x32_bf16 v[122:125], v[156:159], v[192:195], v[122:125]
	v_mfma_f32_16x16x32_bf16 v[122:125], v[152:155], v[188:191], v[122:125]
	v_mfma_f32_16x16x32_bf16 v[106:109], v[152:155], v[196:199], v[106:109]
	v_mfma_f32_16x16x32_bf16 v[106:109], v[156:159], v[200:203], v[106:109]
	v_mfma_f32_16x16x32_bf16 v[110:113], v[134:137], v[200:203], v[110:113]
	v_mfma_f32_16x16x32_bf16 v[110:113], v[130:133], v[196:199], v[110:113]
	v_mfma_f32_16x16x32_bf16 v[94:97], v[130:133], v[204:207], v[94:97]
	v_mfma_f32_16x16x32_bf16 v[94:97], v[134:137], v[208:211], v[94:97]
	v_mfma_f32_16x16x32_bf16 v[90:93], v[156:159], v[208:211], v[90:93]
	v_mfma_f32_16x16x32_bf16 v[90:93], v[152:155], v[204:207], v[90:93]
	v_mfma_f32_16x16x32_bf16 v[74:77], v[152:155], v[212:215], v[74:77]
	v_mfma_f32_16x16x32_bf16 v[74:77], v[156:159], v[216:219], v[74:77]
	v_mfma_f32_16x16x32_bf16 v[78:81], v[134:137], v[216:219], v[78:81]
	v_mfma_f32_16x16x32_bf16 v[78:81], v[130:133], v[212:215], v[78:81]
	s_setprio 0
	s_setprio 1
	v_mfma_f32_16x16x32_bf16 v[70:73], v[166:169], v[212:215], v[70:73]
	v_mfma_f32_16x16x32_bf16 v[70:73], v[170:173], v[216:219], v[70:73]
	v_mfma_f32_16x16x32_bf16 v[66:69], v[182:185], v[216:219], v[66:69]
	v_mfma_f32_16x16x32_bf16 v[66:69], v[174:177], v[212:215], v[66:69]
	v_mfma_f32_16x16x32_bf16 v[82:85], v[174:177], v[204:207], v[82:85]
	v_mfma_f32_16x16x32_bf16 v[82:85], v[182:185], v[208:211], v[82:85]
	v_mfma_f32_16x16x32_bf16 v[86:89], v[170:173], v[208:211], v[86:89]
	v_mfma_f32_16x16x32_bf16 v[86:89], v[166:169], v[204:207], v[86:89]
	v_mfma_f32_16x16x32_bf16 v[102:105], v[166:169], v[196:199], v[102:105]
	v_mfma_f32_16x16x32_bf16 v[102:105], v[170:173], v[200:203], v[102:105]
	v_mfma_f32_16x16x32_bf16 v[98:101], v[182:185], v[200:203], v[98:101]
	v_mfma_f32_16x16x32_bf16 v[98:101], v[174:177], v[196:199], v[98:101]
	v_mfma_f32_16x16x32_bf16 v[114:117], v[174:177], v[188:191], v[114:117]
	v_mfma_f32_16x16x32_bf16 v[114:117], v[182:185], v[192:195], v[114:117]
	v_mfma_f32_16x16x32_bf16 v[118:121], v[170:173], v[192:195], v[118:121]
	v_mfma_f32_16x16x32_bf16 v[118:121], v[166:169], v[188:191], v[118:121]
	s_setprio 0
	s_barrier
	s_add_i32 s90, s83, s15
	v_lshl_add_u64 v[178:179], s[60:61], 0, v[138:139]
	s_mov_b32 m0, s90
	ds_read_b128 v[188:191], v163 offset:16384
	ds_read_b128 v[192:195], v163 offset:17408
	ds_read_b128 v[196:199], v163 offset:18432
	ds_read_b128 v[200:203], v163 offset:19456
	ds_read_b128 v[204:207], v163 offset:20480
	ds_read_b128 v[208:211], v163 offset:21504
	ds_read_b128 v[212:215], v163 offset:22528
	ds_read_b128 v[216:219], v163 offset:23552
	global_load_lds_dwordx4 v[178:179], off
	s_add_i32 m0, s90, 0x2000
	s_add_u32 s90, s60, 0x80000
	v_lshl_add_u64 v[178:179], s[60:61], 0, v[140:141]
	s_addc_u32 s91, s61, 0
	s_add_i32 s92, s86, s15
	global_load_lds_dwordx4 v[178:179], off
	v_lshl_add_u64 v[178:179], s[90:91], 0, v[138:139]
	s_mov_b32 m0, s92
	s_nop 0
	global_load_lds_dwordx4 v[178:179], off
	v_lshl_add_u64 v[178:179], s[90:91], 0, v[140:141]
	s_add_i32 m0, s92, 0x2000
	s_nop 0
	global_load_lds_dwordx4 v[178:179], off
	v_lshl_add_u64 v[178:179], s[70:71], 0, v[138:139]
	s_mov_b32 m0, s72
	s_nop 0
	global_load_lds_dwordx4 v[178:179], off
	v_lshl_add_u64 v[178:179], s[70:71], 0, v[140:141]
	s_mov_b32 m0, s73
	s_nop 0
	global_load_lds_dwordx4 v[178:179], off
	s_waitcnt vmcnt(8)
	s_waitcnt lgkmcnt(0)
	s_barrier
	s_setprio 1
	s_waitcnt lgkmcnt(0)
	v_mfma_f32_16x16x32_bf16 v[62:65], v[130:133], v[188:191], v[62:65]
	v_mfma_f32_16x16x32_bf16 v[62:65], v[134:137], v[192:195], v[62:65]
	v_mfma_f32_16x16x32_bf16 v[58:61], v[156:159], v[192:195], v[58:61]
	v_mfma_f32_16x16x32_bf16 v[58:61], v[152:155], v[188:191], v[58:61]
	v_mfma_f32_16x16x32_bf16 v[42:45], v[152:155], v[196:199], v[42:45]
	v_mfma_f32_16x16x32_bf16 v[42:45], v[156:159], v[200:203], v[42:45]
	v_mfma_f32_16x16x32_bf16 v[46:49], v[134:137], v[200:203], v[46:49]
	v_mfma_f32_16x16x32_bf16 v[46:49], v[130:133], v[196:199], v[46:49]
	v_mfma_f32_16x16x32_bf16 v[30:33], v[130:133], v[204:207], v[30:33]
	v_mfma_f32_16x16x32_bf16 v[30:33], v[134:137], v[208:211], v[30:33]
	v_mfma_f32_16x16x32_bf16 v[26:29], v[156:159], v[208:211], v[26:29]
	v_mfma_f32_16x16x32_bf16 v[26:29], v[152:155], v[204:207], v[26:29]
	v_mfma_f32_16x16x32_bf16 v[10:13], v[152:155], v[212:215], v[10:13]
	v_mfma_f32_16x16x32_bf16 v[10:13], v[156:159], v[216:219], v[10:13]
	v_mfma_f32_16x16x32_bf16 v[14:17], v[134:137], v[216:219], v[14:17]
	v_mfma_f32_16x16x32_bf16 v[14:17], v[130:133], v[212:215], v[14:17]
	s_setprio 0
	s_setprio 1
	v_mfma_f32_16x16x32_bf16 v[6:9], v[166:169], v[212:215], v[6:9]
	v_mfma_f32_16x16x32_bf16 v[6:9], v[170:173], v[216:219], v[6:9]
	v_mfma_f32_16x16x32_bf16 v[2:5], v[182:185], v[216:219], v[2:5]
	v_mfma_f32_16x16x32_bf16 v[2:5], v[174:177], v[212:215], v[2:5]
	v_mfma_f32_16x16x32_bf16 v[18:21], v[174:177], v[204:207], v[18:21]
	v_mfma_f32_16x16x32_bf16 v[18:21], v[182:185], v[208:211], v[18:21]
	v_mfma_f32_16x16x32_bf16 v[22:25], v[170:173], v[208:211], v[22:25]
	v_mfma_f32_16x16x32_bf16 v[22:25], v[166:169], v[204:207], v[22:25]
	v_mfma_f32_16x16x32_bf16 v[38:41], v[166:169], v[196:199], v[38:41]
	v_mfma_f32_16x16x32_bf16 v[38:41], v[170:173], v[200:203], v[38:41]
	v_mfma_f32_16x16x32_bf16 v[34:37], v[182:185], v[200:203], v[34:37]
	v_mfma_f32_16x16x32_bf16 v[34:37], v[174:177], v[196:199], v[34:37]
	v_mfma_f32_16x16x32_bf16 v[50:53], v[174:177], v[188:191], v[50:53]
	v_mfma_f32_16x16x32_bf16 v[50:53], v[182:185], v[192:195], v[50:53]
	v_mfma_f32_16x16x32_bf16 v[54:57], v[170:173], v[192:195], v[54:57]
	v_mfma_f32_16x16x32_bf16 v[54:57], v[166:169], v[188:191], v[54:57]
	s_setprio 0
	s_barrier
; #define PG8_STAGE(bufoff, gbase, voff) do { _Pragma("unroll") for (int _i = 0; _i < 2; ++_i) \
;         __builtin_amdgcn_global_load_lds((const unsigned*)((const char*)(gbase) + (voff)[_i]), (PG8_LAS unsigned*)(lds + (bufoff) + ldsw + _i * 8192), 16, 0, 0); } while (0)
; #define PG8_LDA(dst, b, h) do { _Pragma("unroll") for (int m = 0; m < 4; ++m) _Pragma("unroll") for (int k = 0; k < 2; ++k) dst[m][k] = *(const PG8_LAS bf16x8*)(lds + PG8_SA(b, h) + aoff + m * 2048 + k * 1024); } while (0)
; #define PG8_LDB(dst, b, h) do { _Pragma("unroll") for (int n = 0; n < 2; ++n) _Pragma("unroll") for (int k = 0; k < 2; ++k) dst[n][k] = *(const PG8_LAS bf16x8*)(lds + PG8_SB(b, h) + boff + n * 2048 + k * 1024); } while (0)
; #define PG8_WAIT_V(n) asm volatile("s_waitcnt vmcnt(" #n ")" ::: "memory")
; #define PG8_WAIT_L(n) asm volatile("s_waitcnt lgkmcnt(" #n ")" ::: "memory")
; #define PG8_BAR __builtin_amdgcn_s_barrier()
; #define PG8_SCHED __builtin_amdgcn_sched_barrier(0)
; template <class Epi, class Sched, bool ALIGN_EPI = false, bool SP2 = false, bool RS = false, bool BPRE = false>
; __device__ __forceinline__ void gemm_phase(PG8_LAS unsigned char* lds, const Gemm g, const Sched& S, const Epi& E, const float* rs_ss = nullptr, PG8_LAS float* rs_tab = nullptr) {
;     ...
;             PG8_LDB(B0, 0, 0); PG8_LDB(B1, 0, 1); PG8_SCHED; PG8_LDA(At, 0, 0); PG8_STAGE(PG8_SA(1, 1), a1 + hstep, voffA);
;             PG8_WAIT_V(8); PG8_WAIT_L(0); PG8_BAR; PG8_MMA(0, 0, At, B0); PG8_MMA(0, 1, At, B1); PG8_BAR; PG8_SCHED;
;             PG8_LDA(At, 0, 1); PG8_STAGE(PG8_SB(0, 0), b2, voffB); PG8_STAGE(PG8_SB(0, 1), b2 + hstep, voffB); PG8_STAGE(PG8_SA(0, 0), a2, voffA);
;             PG8_WAIT_V(8); PG8_WAIT_L(0); PG8_BAR; PG8_MMA(1, 0, At, B0); PG8_MMA(1, 1, At, B1); PG8_BAR; PG8_SCHED;
;             PG8_LDB(B0, 1, 0); PG8_LDB(B1, 1, 1); PG8_SCHED; PG8_LDA(At, 1, 0); PG8_STAGE(PG8_SA(0, 1), a2 + hstep, voffA);
;             PG8_WAIT_V(8); PG8_WAIT_L(0); PG8_BAR; PG8_MMA(0, 0, At, B0); PG8_MMA(0, 1, At, B1); PG8_BAR; PG8_SCHED;
;             PG8_LDA(At, 1, 1); PG8_STAGE(PG8_SB(1, 0), b3, voffB); PG8_STAGE(PG8_SB(1, 1), b3 + hstep, voffB); PG8_STAGE(PG8_SA(1, 0), a3, voffA);
;             PG8_WAIT_V(8); PG8_WAIT_L(0); PG8_BAR; PG8_MMA(1, 0, At, B0); PG8_MMA(1, 1, At, B1); PG8_BAR; PG8_SCHED;
	s_add_i32 s90, 0, 0x18000
	v_add_u32_e32 v143, s90, v160
	s_add_i32 s91, 0, 0x1c000
	ds_read_b128 v[130:133], v143
	ds_read_b128 v[134:137], v143 offset:1024
	ds_read_b128 v[152:155], v143 offset:2048
	ds_read_b128 v[156:159], v143 offset:3072
	v_add_u32_e32 v143, s91, v160
	ds_read_b128 v[166:169], v143
	ds_read_b128 v[170:173], v143 offset:1024
	ds_read_b128 v[174:177], v143 offset:2048
	ds_read_b128 v[182:185], v143 offset:3072
	s_add_u32 s70, s70, 0x80000
	s_addc_u32 s71, s71, 0
	s_mov_b32 m0, s74
	v_lshl_add_u64 v[178:179], s[70:71], 0, v[138:139]
	ds_read_b128 v[188:191], v163 offset:32768
	ds_read_b128 v[192:195], v163 offset:33792
	ds_read_b128 v[196:199], v163 offset:34816
	ds_read_b128 v[200:203], v163 offset:35840
	ds_read_b128 v[204:207], v163 offset:36864
	ds_read_b128 v[208:211], v163 offset:37888
	ds_read_b128 v[212:215], v163 offset:38912
	ds_read_b128 v[216:219], v163 offset:39936
	global_load_lds_dwordx4 v[178:179], off
	v_lshl_add_u64 v[178:179], s[70:71], 0, v[140:141]
	s_mov_b32 m0, s75
	s_nop 0
	global_load_lds_dwordx4 v[178:179], off
	s_waitcnt vmcnt(8)
	s_waitcnt lgkmcnt(0)
	s_barrier
	s_setprio 1
	s_waitcnt lgkmcnt(0)
	v_mfma_f32_16x16x32_bf16 v[126:129], v[130:133], v[188:191], v[126:129]
	v_mfma_f32_16x16x32_bf16 v[126:129], v[134:137], v[192:195], v[126:129]
	v_mfma_f32_16x16x32_bf16 v[122:125], v[156:159], v[192:195], v[122:125]
	v_mfma_f32_16x16x32_bf16 v[122:125], v[152:155], v[188:191], v[122:125]
	v_mfma_f32_16x16x32_bf16 v[106:109], v[152:155], v[196:199], v[106:109]
	v_mfma_f32_16x16x32_bf16 v[106:109], v[156:159], v[200:203], v[106:109]
	v_mfma_f32_16x16x32_bf16 v[110:113], v[134:137], v[200:203], v[110:113]
	v_mfma_f32_16x16x32_bf16 v[110:113], v[130:133], v[196:199], v[110:113]
	v_mfma_f32_16x16x32_bf16 v[94:97], v[130:133], v[204:207], v[94:97]
	v_mfma_f32_16x16x32_bf16 v[94:97], v[134:137], v[208:211], v[94:97]
	v_mfma_f32_16x16x32_bf16 v[90:93], v[156:159], v[208:211], v[90:93]
	v_mfma_f32_16x16x32_bf16 v[90:93], v[152:155], v[204:207], v[90:93]
	v_mfma_f32_16x16x32_bf16 v[74:77], v[152:155], v[212:215], v[74:77]
	v_mfma_f32_16x16x32_bf16 v[74:77], v[156:159], v[216:219], v[74:77]
	v_mfma_f32_16x16x32_bf16 v[78:81], v[134:137], v[216:219], v[78:81]
	v_mfma_f32_16x16x32_bf16 v[78:81], v[130:133], v[212:215], v[78:81]
	s_setprio 0
	s_setprio 1
	v_mfma_f32_16x16x32_bf16 v[70:73], v[166:169], v[212:215], v[70:73]
	v_mfma_f32_16x16x32_bf16 v[70:73], v[170:173], v[216:219], v[70:73]
	v_mfma_f32_16x16x32_bf16 v[66:69], v[182:185], v[216:219], v[66:69]
	v_mfma_f32_16x16x32_bf16 v[66:69], v[174:177], v[212:215], v[66:69]
	v_mfma_f32_16x16x32_bf16 v[82:85], v[174:177], v[204:207], v[82:85]
	v_mfma_f32_16x16x32_bf16 v[82:85], v[182:185], v[208:211], v[82:85]
	v_mfma_f32_16x16x32_bf16 v[86:89], v[170:173], v[208:211], v[86:89]
	v_mfma_f32_16x16x32_bf16 v[86:89], v[166:169], v[204:207], v[86:89]
	v_mfma_f32_16x16x32_bf16 v[102:105], v[166:169], v[196:199], v[102:105]
	v_mfma_f32_16x16x32_bf16 v[102:105], v[170:173], v[200:203], v[102:105]
	v_mfma_f32_16x16x32_bf16 v[98:101], v[182:185], v[200:203], v[98:101]
	v_mfma_f32_16x16x32_bf16 v[98:101], v[174:177], v[196:199], v[98:101]
	v_mfma_f32_16x16x32_bf16 v[114:117], v[174:177], v[188:191], v[114:117]
	v_mfma_f32_16x16x32_bf16 v[114:117], v[182:185], v[192:195], v[114:117]
	v_mfma_f32_16x16x32_bf16 v[118:121], v[170:173], v[192:195], v[118:121]
	v_mfma_f32_16x16x32_bf16 v[118:121], v[166:169], v[188:191], v[118:121]
	s_setprio 0
	s_barrier
	s_add_u32 s70, s60, 0x4000
	s_addc_u32 s71, s61, 0
	s_add_i32 s90, s90, s15
	v_lshl_add_u64 v[178:179], s[70:71], 0, v[138:139]
	s_mov_b32 m0, s90
	ds_read_b128 v[188:191], v163 offset:49152
	ds_read_b128 v[192:195], v163 offset:50176
	ds_read_b128 v[196:199], v163 offset:51200
	ds_read_b128 v[200:203], v163 offset:52224
	ds_read_b128 v[204:207], v163 offset:53248
	ds_read_b128 v[208:211], v163 offset:54272
	ds_read_b128 v[212:215], v163 offset:55296
	ds_read_b128 v[216:219], v163 offset:56320
	global_load_lds_dwordx4 v[178:179], off
	s_add_i32 m0, s90, 0x2000
	s_add_u32 s60, s60, 0x84000
	v_lshl_add_u64 v[178:179], s[70:71], 0, v[140:141]
	s_addc_u32 s61, s61, 0
	s_add_i32 s70, s91, s15
	global_load_lds_dwordx4 v[178:179], off
	v_lshl_add_u64 v[178:179], s[60:61], 0, v[138:139]
	s_mov_b32 m0, s70
	s_nop 0
	global_load_lds_dwordx4 v[178:179], off
	v_lshl_add_u64 v[178:179], s[60:61], 0, v[140:141]
	s_add_i32 m0, s70, 0x2000
	s_nop 0
	global_load_lds_dwordx4 v[178:179], off
	v_lshl_add_u64 v[178:179], s[58:59], 0, v[138:139]
	s_mov_b32 m0, s79
	s_nop 0
	global_load_lds_dwordx4 v[178:179], off
	v_lshl_add_u64 v[178:179], s[58:59], 0, v[140:141]
	s_mov_b32 m0, s80
	s_nop 0
	global_load_lds_dwordx4 v[178:179], off
	s_waitcnt vmcnt(8)
	s_waitcnt lgkmcnt(0)
	s_barrier
; #define PG8_BAR __builtin_amdgcn_s_barrier()
; template <class Epi, class Sched, bool ALIGN_EPI = false, bool SP2 = false, bool RS = false, bool BPRE = false>
; __device__ __forceinline__ void gemm_phase(PG8_LAS unsigned char* lds, const Gemm g, const Sched& S, const Epi& E, const float* rs_ss = nullptr, PG8_LAS float* rs_tab = nullptr) {
;     ...
;             PG8_WAIT_V(8); PG8_WAIT_L(0); PG8_BAR; PG8_MMA(1, 0, At, B0); PG8_MMA(1, 1, At, B1); PG8_BAR; PG8_SCHED;
;             PG8_LDB(B0, 1, 0); PG8_LDB(B1, 1, 1); PG8_SCHED; PG8_LDA(At, 1, 0); PG8_STAGE(PG8_SA(0, 1), a2 + hstep, voffA);
;             PG8_WAIT_V(8); PG8_WAIT_L(0); PG8_BAR; PG8_MMA(0, 0, At, B0); PG8_MMA(0, 1, At, B1); PG8_BAR; PG8_SCHED;
;             PG8_LDA(At, 1, 1); PG8_STAGE(PG8_SB(1, 0), b3, voffB); PG8_STAGE(PG8_SB(1, 1), b3 + hstep, voffB); PG8_STAGE(PG8_SA(1, 0), a3, voffA);
;             PG8_WAIT_V(8); PG8_WAIT_L(0); PG8_BAR; PG8_MMA(1, 0, At, B0); PG8_MMA(1, 1, At, B1); PG8_BAR; PG8_SCHED;
;     __device__ __forceinline__ void operator()(const f32x4 (&acc)[2][2][4][2], const pg8::Unit& u, int wr, int wc, int fr, int fq, const LAS float* tab) const {
;         int kind = 0, pm = u.pm, pn = u.pn, ldc = INW; bf16_t* base = O;
;         if (mode == 0) { const int seg = pn >> 2; kind = (seg == 1 || seg == 4 || seg == 6) ? 1 : (seg == 5 ? 2 : (seg == 3 ? 3 : 0)); }
;         else if (mode == 1) { ldc = 256; if (pm >= 8) { pm -= 8; } else { pm -= 4; pn -= 8; base = O2; } base += (size_t)(pm * 4 + pn) * 65536; pm = 0; pn = 0; }
;         else { ldc = DMODEL; kind = 4; }
;         int col0 = pn * 256 + wc * 32 + 8 * fq; const int row0 = pm * 256 + wr * 64 + fr;
;         if (mode == 0) { ldc = 256; base = O + (size_t)pn * NTOK * 256; col0 = wc * 32 + 8 * fq; }
; #pragma unroll
;         for (int ai = 0; ai < 2; ++ai)
; #pragma unroll
;             for (int m = 0; m < 4; ++m) {
;                 const int row = row0 + ai * 128 + m * 16;
;                 bf16_t* rowp = (mode == 0) ? base + (size_t)(row >> 4) * 4096 + (size_t)(wc * 512 + (row & 15) * 32 + 8 * fq) : base + (size_t)row * ldc + col0;
;                 const int bjstep = (mode == 0) ? 4 * 512 : 128;
;                 float s1 = 0.f, s2 = 0.f;
;                 const float f2 = (kind == 4) ? tab[512 + ai * 128 + wr * 64 + m * 16 + fr] : 1.0f;
; #pragma unroll
;                 for (int bj = 0; bj < 2; ++bj) {
	s_setprio 1
	s_waitcnt lgkmcnt(0)
	v_mfma_f32_16x16x32_bf16 v[62:65], v[130:133], v[188:191], v[62:65]
	v_mfma_f32_16x16x32_bf16 v[62:65], v[134:137], v[192:195], v[62:65]
	v_mfma_f32_16x16x32_bf16 v[58:61], v[156:159], v[192:195], v[58:61]
	v_mfma_f32_16x16x32_bf16 v[58:61], v[152:155], v[188:191], v[58:61]
	v_mfma_f32_16x16x32_bf16 v[42:45], v[152:155], v[196:199], v[42:45]
	v_mfma_f32_16x16x32_bf16 v[42:45], v[156:159], v[200:203], v[42:45]
	v_mfma_f32_16x16x32_bf16 v[46:49], v[134:137], v[200:203], v[46:49]
	v_mfma_f32_16x16x32_bf16 v[46:49], v[130:133], v[196:199], v[46:49]
	v_mfma_f32_16x16x32_bf16 v[30:33], v[130:133], v[204:207], v[30:33]
	v_mfma_f32_16x16x32_bf16 v[30:33], v[134:137], v[208:211], v[30:33]
	v_mfma_f32_16x16x32_bf16 v[26:29], v[156:159], v[208:211], v[26:29]
	v_mfma_f32_16x16x32_bf16 v[26:29], v[152:155], v[204:207], v[26:29]
	v_mfma_f32_16x16x32_bf16 v[10:13], v[152:155], v[212:215], v[10:13]
	v_mfma_f32_16x16x32_bf16 v[10:13], v[156:159], v[216:219], v[10:13]
	v_mfma_f32_16x16x32_bf16 v[14:17], v[134:137], v[216:219], v[14:17]
	v_mfma_f32_16x16x32_bf16 v[14:17], v[130:133], v[212:215], v[14:17]
	s_setprio 0
	s_setprio 1
	v_mfma_f32_16x16x32_bf16 v[6:9], v[166:169], v[212:215], v[6:9]
	v_mfma_f32_16x16x32_bf16 v[6:9], v[170:173], v[216:219], v[6:9]
	v_mfma_f32_16x16x32_bf16 v[2:5], v[182:185], v[216:219], v[2:5]
	v_mfma_f32_16x16x32_bf16 v[2:5], v[174:177], v[212:215], v[2:5]
	v_mfma_f32_16x16x32_bf16 v[18:21], v[174:177], v[204:207], v[18:21]
	v_mfma_f32_16x16x32_bf16 v[18:21], v[182:185], v[208:211], v[18:21]
	v_mfma_f32_16x16x32_bf16 v[22:25], v[170:173], v[208:211], v[22:25]
	v_mfma_f32_16x16x32_bf16 v[22:25], v[166:169], v[204:207], v[22:25]
	v_mfma_f32_16x16x32_bf16 v[38:41], v[166:169], v[196:199], v[38:41]
	v_mfma_f32_16x16x32_bf16 v[38:41], v[170:173], v[200:203], v[38:41]
	v_mfma_f32_16x16x32_bf16 v[34:37], v[182:185], v[200:203], v[34:37]
	v_mfma_f32_16x16x32_bf16 v[34:37], v[174:177], v[196:199], v[34:37]
	v_mfma_f32_16x16x32_bf16 v[50:53], v[174:177], v[188:191], v[50:53]
	v_mfma_f32_16x16x32_bf16 v[50:53], v[182:185], v[192:195], v[50:53]
	v_mfma_f32_16x16x32_bf16 v[54:57], v[170:173], v[192:195], v[54:57]
	v_mfma_f32_16x16x32_bf16 v[54:57], v[166:169], v[188:191], v[54:57]
	s_setprio 0
	s_barrier
	s_add_i32 s89, s89, 2
	s_add_u32 s56, s56, 0x8000
	s_addc_u32 s57, s57, 0
	s_add_u32 s87, s87, 0x8000
	s_addc_u32 s88, s88, 0
	s_cmp_gt_u32 s89, 29
	s_cbranch_scc0 .LBB0_196
	s_and_b64 vcc, exec, s[12:13]
	s_cbranch_vccz .LBB0_199
	s_barrier
.LBB0_199:
	v_and_b32_e32 v252, 15, v164
	v_bfe_u32 v253, v164, 4, 2
	v_lshlrev_b32_e32 v252, 6, v252
	v_lshl_or_b32 v252, v253, 4, v252
	s_and_b32 s93, s33, 3
	s_lshl_b32 s94, s93, 10
	v_or_b32_e32 v252, s94, v252
	v_and_b32_e32 v253, 15, v164
	v_lshlrev_b32_e32 v253, 7, v253
	s_lshl_b32 s94, s4, 23
	s_lshl_b32 s95, s46, 4
	s_lshr_b32 s98, s33, 2
	s_lshl_b32 s99, s98, 2
	s_add_i32 s95, s95, s99
	s_lshl_b32 s95, s95, 13
	s_add_u32 s94, s94, s95
	s_add_u32 s96, s36, s94
	s_addc_u32 s97, s37, 0
	s_lshr_b32 s94, s4, 2
	s_cmp_eq_u32 s94, 1
	s_cbranch_scc1 .Lepi_silu
	s_cmp_eq_u32 s94, 4
	s_cbranch_scc1 .Lepi_silu
	s_cmp_eq_u32 s94, 6
	s_cbranch_scc1 .Lepi_silu
	s_cmp_eq_u32 s94, 5
	s_cbranch_scc1 .Lepi_scale
	s_cmp_eq_u32 s94, 3
	s_cbranch_scc1 .Lepi_stats
.Lepi_plain:
	v_cvt_pk_bf16_f32 v232, v126, v127
	v_cvt_pk_bf16_f32 v233, v128, v129
	v_cvt_pk_bf16_f32 v234, v122, v123
	v_cvt_pk_bf16_f32 v235, v124, v125
	global_store_dwordx4 v252, v[232:235], s[96:97]
	s_add_u32 s96, s96, 0x1000
	s_addc_u32 s97, s97, 0
	v_cvt_pk_bf16_f32 v236, v118, v119
	v_cvt_pk_bf16_f32 v237, v120, v121
	v_cvt_pk_bf16_f32 v238, v114, v115
	v_cvt_pk_bf16_f32 v239, v116, v117
	global_store_dwordx4 v252, v[236:239], s[96:97]
	s_add_u32 s96, s96, 0x1000
	s_addc_u32 s97, s97, 0
	v_cvt_pk_bf16_f32 v232, v110, v111
	v_cvt_pk_bf16_f32 v233, v112, v113
	v_cvt_pk_bf16_f32 v234, v106, v107
	v_cvt_pk_bf16_f32 v235, v108, v109
	global_store_dwordx4 v252, v[232:235], s[96:97]
	s_add_u32 s96, s96, 0x1000
	s_addc_u32 s97, s97, 0
	v_cvt_pk_bf16_f32 v236, v102, v103
	v_cvt_pk_bf16_f32 v237, v104, v105
	v_cvt_pk_bf16_f32 v238, v98, v99
	v_cvt_pk_bf16_f32 v239, v100, v101
	global_store_dwordx4 v252, v[236:239], s[96:97]
	s_add_u32 s96, s96, 0x1000
	s_addc_u32 s97, s97, 0
	v_cvt_pk_bf16_f32 v232, v94, v95
	v_cvt_pk_bf16_f32 v233, v96, v97
	v_cvt_pk_bf16_f32 v234, v90, v91
	v_cvt_pk_bf16_f32 v235, v92, v93
	global_store_dwordx4 v252, v[232:235], s[96:97]
	s_add_u32 s96, s96, 0x1000
	s_addc_u32 s97, s97, 0
	v_cvt_pk_bf16_f32 v236, v86, v87
	v_cvt_pk_bf16_f32 v237, v88, v89
	v_cvt_pk_bf16_f32 v238, v82, v83
	v_cvt_pk_bf16_f32 v239, v84, v85
	global_store_dwordx4 v252, v[236:239], s[96:97]
	s_add_u32 s96, s96, 0x1000
	s_addc_u32 s97, s97, 0
	v_cvt_pk_bf16_f32 v232, v78, v79
	v_cvt_pk_bf16_f32 v233, v80, v81
	v_cvt_pk_bf16_f32 v234, v74, v75
	v_cvt_pk_bf16_f32 v235, v76, v77
	global_store_dwordx4 v252, v[232:235], s[96:97]
	s_add_u32 s96, s96, 0x1000
	s_addc_u32 s97, s97, 0
	v_cvt_pk_bf16_f32 v236, v70, v71
	v_cvt_pk_bf16_f32 v237, v72, v73
	v_cvt_pk_bf16_f32 v238, v66, v67
	v_cvt_pk_bf16_f32 v239, v68, v69
	global_store_dwordx4 v252, v[236:239], s[96:97]
	s_add_u32 s96, s96, 0x1000
	s_addc_u32 s97, s97, 0
	s_add_u32 s96, s96, 0x8000
	s_addc_u32 s97, s97, 0
	v_cvt_pk_bf16_f32 v232, v62, v63
	v_cvt_pk_bf16_f32 v233, v64, v65
	v_cvt_pk_bf16_f32 v234, v58, v59
	v_cvt_pk_bf16_f32 v235, v60, v61
	global_store_dwordx4 v252, v[232:235], s[96:97]
	s_add_u32 s96, s96, 0x1000
	s_addc_u32 s97, s97, 0
	v_cvt_pk_bf16_f32 v236, v54, v55
	v_cvt_pk_bf16_f32 v237, v56, v57
	v_cvt_pk_bf16_f32 v238, v50, v51
	v_cvt_pk_bf16_f32 v239, v52, v53
; #define LAS __attribute__((address_space(3)))
; __device__ __forceinline__ float silu_f(float x) { return x * __builtin_amdgcn_rcpf(1.0f + __builtin_amdgcn_exp2f(-x * LOG2E)); }
;     __device__ __forceinline__ void operator()(const f32x4 (&acc)[2][2][4][2], const pg8::Unit& u, int wr, int wc, int fr, int fq, const LAS float* tab) const {
;         int kind = 0, pm = u.pm, pn = u.pn, ldc = INW; bf16_t* base = O;
;         if (mode == 0) { const int seg = pn >> 2; kind = (seg == 1 || seg == 4 || seg == 6) ? 1 : (seg == 5 ? 2 : (seg == 3 ? 3 : 0)); }
;         else if (mode == 1) { ldc = 256; if (pm >= 8) { pm -= 8; } else { pm -= 4; pn -= 8; base = O2; } base += (size_t)(pm * 4 + pn) * 65536; pm = 0; pn = 0; }
;         else { ldc = DMODEL; kind = 4; }
;         int col0 = pn * 256 + wc * 32 + 8 * fq; const int row0 = pm * 256 + wr * 64 + fr;
;         if (mode == 0) { ldc = 256; base = O + (size_t)pn * NTOK * 256; col0 = wc * 32 + 8 * fq; }
; #pragma unroll
;         for (int ai = 0; ai < 2; ++ai)
; #pragma unroll
;             for (int m = 0; m < 4; ++m) {
;                 const int row = row0 + ai * 128 + m * 16;
;                 bf16_t* rowp = (mode == 0) ? base + (size_t)(row >> 4) * 4096 + (size_t)(wc * 512 + (row & 15) * 32 + 8 * fq) : base + (size_t)row * ldc + col0;
;                 const int bjstep = (mode == 0) ? 4 * 512 : 128;
;                 float s1 = 0.f, s2 = 0.f;
;                 const float f2 = (kind == 4) ? tab[512 + ai * 128 + wr * 64 + m * 16 + fr] : 1.0f;
; #pragma unroll
;                 for (int bj = 0; bj < 2; ++bj) {
;                     f32x4 v0 = acc[ai][bj][m][0], v1 = acc[ai][bj][m][1];
;                     if (kind == 1) {
; #pragma unroll
;                         for (int e = 0; e < 4; ++e) { v0[e] = silu_f(v0[e]); v1[e] = silu_f(v1[e]); }
;                     } else if (kind == 2) { v0 = v0 * QSCALE; v1 = v1 * QSCALE; }
;                     else if (kind == 3) {
; #pragma unroll
;                         for (int e = 0; e < 4; ++e) { s1 += v0[e] + v1[e]; s2 += v0[e] * v0[e] + v1[e] * v1[e]; }
;                     } else if (kind == 4) {
;                         v0 = v0 * f2; v1 = v1 * f2;
; #pragma unroll
;                         for (int e = 0; e < 4; ++e) s2 += v0[e] * v0[e] + v1[e] * v1[e];
;                     }
	global_store_dwordx4 v252, v[236:239], s[96:97]
	s_add_u32 s96, s96, 0x1000
	s_addc_u32 s97, s97, 0
	v_cvt_pk_bf16_f32 v232, v46, v47
	v_cvt_pk_bf16_f32 v233, v48, v49
	v_cvt_pk_bf16_f32 v234, v42, v43
	v_cvt_pk_bf16_f32 v235, v44, v45
	global_store_dwordx4 v252, v[232:235], s[96:97]
	s_add_u32 s96, s96, 0x1000
	s_addc_u32 s97, s97, 0
	v_cvt_pk_bf16_f32 v236, v38, v39
	v_cvt_pk_bf16_f32 v237, v40, v41
	v_cvt_pk_bf16_f32 v238, v34, v35
	v_cvt_pk_bf16_f32 v239, v36, v37
	global_store_dwordx4 v252, v[236:239], s[96:97]
	s_add_u32 s96, s96, 0x1000
	s_addc_u32 s97, s97, 0
	v_cvt_pk_bf16_f32 v232, v30, v31
	v_cvt_pk_bf16_f32 v233, v32, v33
	v_cvt_pk_bf16_f32 v234, v26, v27
	v_cvt_pk_bf16_f32 v235, v28, v29
	global_store_dwordx4 v252, v[232:235], s[96:97]
	s_add_u32 s96, s96, 0x1000
	s_addc_u32 s97, s97, 0
	v_cvt_pk_bf16_f32 v236, v22, v23
	v_cvt_pk_bf16_f32 v237, v24, v25
	v_cvt_pk_bf16_f32 v238, v18, v19
	v_cvt_pk_bf16_f32 v239, v20, v21
	global_store_dwordx4 v252, v[236:239], s[96:97]
	s_add_u32 s96, s96, 0x1000
	s_addc_u32 s97, s97, 0
	v_cvt_pk_bf16_f32 v232, v14, v15
	v_cvt_pk_bf16_f32 v233, v16, v17
	v_cvt_pk_bf16_f32 v234, v10, v11
	v_cvt_pk_bf16_f32 v235, v12, v13
	global_store_dwordx4 v252, v[232:235], s[96:97]
	s_add_u32 s96, s96, 0x1000
	s_addc_u32 s97, s97, 0
	v_cvt_pk_bf16_f32 v236, v6, v7
	v_cvt_pk_bf16_f32 v237, v8, v9
	v_cvt_pk_bf16_f32 v238, v2, v3
	v_cvt_pk_bf16_f32 v239, v4, v5
	global_store_dwordx4 v252, v[236:239], s[96:97]
	s_add_u32 s96, s96, 0x1000
	s_addc_u32 s97, s97, 0
	s_branch .LBB0_391
.Lepi_silu:
	v_mov_b32_e32 v220, 0xbfb8aa3b
	v_mov_b32_e32 v221, 0xbfb8aa3b
	v_mov_b32_e32 v222, 1.0
	v_mov_b32_e32 v223, 1.0
	v_pk_mul_f32 v[224:225], v[126:127], v[220:221]
	v_pk_mul_f32 v[226:227], v[128:129], v[220:221]
	v_pk_mul_f32 v[228:229], v[122:123], v[220:221]
	v_pk_mul_f32 v[230:231], v[124:125], v[220:221]
	v_exp_f32_e32 v224, v224
	v_exp_f32_e32 v225, v225
	v_exp_f32_e32 v226, v226
	v_exp_f32_e32 v227, v227
	v_exp_f32_e32 v228, v228
	v_exp_f32_e32 v229, v229
	v_exp_f32_e32 v230, v230
	v_exp_f32_e32 v231, v231
	v_pk_add_f32 v[224:225], v[224:225], v[222:223]
	v_pk_add_f32 v[226:227], v[226:227], v[222:223]
	v_pk_add_f32 v[228:229], v[228:229], v[222:223]
	v_pk_add_f32 v[230:231], v[230:231], v[222:223]
	v_rcp_f32_e32 v224, v224
	v_rcp_f32_e32 v225, v225
	v_rcp_f32_e32 v226, v226
	v_rcp_f32_e32 v227, v227
	v_rcp_f32_e32 v228, v228
	v_rcp_f32_e32 v229, v229
	v_rcp_f32_e32 v230, v230
	v_rcp_f32_e32 v231, v231
	v_pk_mul_f32 v[126:127], v[126:127], v[224:225]
	v_pk_mul_f32 v[128:129], v[128:129], v[226:227]
	v_pk_mul_f32 v[122:123], v[122:123], v[228:229]
	v_pk_mul_f32 v[124:125], v[124:125], v[230:231]
	v_cvt_pk_bf16_f32 v232, v126, v127
	v_cvt_pk_bf16_f32 v233, v128, v129
	v_cvt_pk_bf16_f32 v234, v122, v123
	v_cvt_pk_bf16_f32 v235, v124, v125
	global_store_dwordx4 v252, v[232:235], s[96:97]
	s_add_u32 s96, s96, 0x1000
	s_addc_u32 s97, s97, 0
	v_pk_mul_f32 v[224:225], v[118:119], v[220:221]
	v_pk_mul_f32 v[226:227], v[120:121], v[220:221]
	v_pk_mul_f32 v[228:229], v[114:115], v[220:221]
	v_pk_mul_f32 v[230:231], v[116:117], v[220:221]
	v_exp_f32_e32 v224, v224
	v_exp_f32_e32 v225, v225
	v_exp_f32_e32 v226, v226
	v_exp_f32_e32 v227, v227
	v_exp_f32_e32 v228, v228
	v_exp_f32_e32 v229, v229
	v_exp_f32_e32 v230, v230
	v_exp_f32_e32 v231, v231
	v_pk_add_f32 v[224:225], v[224:225], v[222:223]
	v_pk_add_f32 v[226:227], v[226:227], v[222:223]
	v_pk_add_f32 v[228:229], v[228:229], v[222:223]
	v_pk_add_f32 v[230:231], v[230:231], v[222:223]
	v_rcp_f32_e32 v224, v224
	v_rcp_f32_e32 v225, v225
	v_rcp_f32_e32 v226, v226
	v_rcp_f32_e32 v227, v227
	v_rcp_f32_e32 v228, v228
	v_rcp_f32_e32 v229, v229
	v_rcp_f32_e32 v230, v230
	v_rcp_f32_e32 v231, v231
	v_pk_mul_f32 v[118:119], v[118:119], v[224:225]
	v_pk_mul_f32 v[120:121], v[120:121], v[226:227]
	v_pk_mul_f32 v[114:115], v[114:115], v[228:229]
	v_pk_mul_f32 v[116:117], v[116:117], v[230:231]
	v_cvt_pk_bf16_f32 v236, v118, v119
	v_cvt_pk_bf16_f32 v237, v120, v121
	v_cvt_pk_bf16_f32 v238, v114, v115
	v_cvt_pk_bf16_f32 v239, v116, v117
	global_store_dwordx4 v252, v[236:239], s[96:97]
	s_add_u32 s96, s96, 0x1000
	s_addc_u32 s97, s97, 0
	v_pk_mul_f32 v[224:225], v[110:111], v[220:221]
	v_pk_mul_f32 v[226:227], v[112:113], v[220:221]
	v_pk_mul_f32 v[228:229], v[106:107], v[220:221]
	v_pk_mul_f32 v[230:231], v[108:109], v[220:221]
	v_exp_f32_e32 v224, v224
	v_exp_f32_e32 v225, v225
	v_exp_f32_e32 v226, v226
	v_exp_f32_e32 v227, v227
	v_exp_f32_e32 v228, v228
	v_exp_f32_e32 v229, v229
	v_exp_f32_e32 v230, v230
	v_exp_f32_e32 v231, v231
	v_pk_add_f32 v[224:225], v[224:225], v[222:223]
	v_pk_add_f32 v[226:227], v[226:227], v[222:223]
	v_pk_add_f32 v[228:229], v[228:229], v[222:223]
	v_pk_add_f32 v[230:231], v[230:231], v[222:223]
	v_rcp_f32_e32 v224, v224
	v_rcp_f32_e32 v225, v225
	v_rcp_f32_e32 v226, v226
	v_rcp_f32_e32 v227, v227
	v_rcp_f32_e32 v228, v228
	v_rcp_f32_e32 v229, v229
	v_rcp_f32_e32 v230, v230
	v_rcp_f32_e32 v231, v231
	v_pk_mul_f32 v[110:111], v[110:111], v[224:225]
	v_pk_mul_f32 v[112:113], v[112:113], v[226:227]
	v_pk_mul_f32 v[106:107], v[106:107], v[228:229]
	v_pk_mul_f32 v[108:109], v[108:109], v[230:231]
	v_cvt_pk_bf16_f32 v232, v110, v111
	v_cvt_pk_bf16_f32 v233, v112, v113
	v_cvt_pk_bf16_f32 v234, v106, v107
	v_cvt_pk_bf16_f32 v235, v108, v109
	global_store_dwordx4 v252, v[232:235], s[96:97]
	s_add_u32 s96, s96, 0x1000
	s_addc_u32 s97, s97, 0
	v_pk_mul_f32 v[224:225], v[102:103], v[220:221]
	v_pk_mul_f32 v[226:227], v[104:105], v[220:221]
	v_pk_mul_f32 v[228:229], v[98:99], v[220:221]
	v_pk_mul_f32 v[230:231], v[100:101], v[220:221]
	v_exp_f32_e32 v224, v224
; __device__ __forceinline__ unsigned cvt_pk_bf16(float lo, float hi) { unsigned r; asm volatile("v_cvt_pk_bf16_f32 %0, %1, %2" : "=v"(r) : "v"(lo), "v"(hi)); return r; }
; __device__ __forceinline__ float silu_f(float x) { return x * __builtin_amdgcn_rcpf(1.0f + __builtin_amdgcn_exp2f(-x * LOG2E)); }
;     __device__ __forceinline__ void operator()(const f32x4 (&acc)[2][2][4][2], const pg8::Unit& u, int wr, int wc, int fr, int fq, const LAS float* tab) const {
;     ...
;                 for (int bj = 0; bj < 2; ++bj) {
;                     f32x4 v0 = acc[ai][bj][m][0], v1 = acc[ai][bj][m][1];
;                     if (kind == 1) {
; #pragma unroll
;                         for (int e = 0; e < 4; ++e) { v0[e] = silu_f(v0[e]); v1[e] = silu_f(v1[e]); }
;                     } else if (kind == 2) { v0 = v0 * QSCALE; v1 = v1 * QSCALE; }
;                     else if (kind == 3) {
; #pragma unroll
;                         for (int e = 0; e < 4; ++e) { s1 += v0[e] + v1[e]; s2 += v0[e] * v0[e] + v1[e] * v1[e]; }
;                     } else if (kind == 4) {
;                         v0 = v0 * f2; v1 = v1 * f2;
; #pragma unroll
;                         for (int e = 0; e < 4; ++e) s2 += v0[e] * v0[e] + v1[e] * v1[e];
;                     }
;                     u32x4 w; w.x = cvt_pk_bf16(v0[0], v0[1]); w.y = cvt_pk_bf16(v0[2], v0[3]); w.z = cvt_pk_bf16(v1[0], v1[1]); w.w = cvt_pk_bf16(v1[2], v1[3]);
;                     *(u32x4*)(rowp + bj * bjstep) = w;
	v_exp_f32_e32 v225, v225
	v_exp_f32_e32 v226, v226
	v_exp_f32_e32 v227, v227
	v_exp_f32_e32 v228, v228
	v_exp_f32_e32 v229, v229
	v_exp_f32_e32 v230, v230
	v_exp_f32_e32 v231, v231
	v_pk_add_f32 v[224:225], v[224:225], v[222:223]
	v_pk_add_f32 v[226:227], v[226:227], v[222:223]
	v_pk_add_f32 v[228:229], v[228:229], v[222:223]
	v_pk_add_f32 v[230:231], v[230:231], v[222:223]
	v_rcp_f32_e32 v224, v224
	v_rcp_f32_e32 v225, v225
	v_rcp_f32_e32 v226, v226
	v_rcp_f32_e32 v227, v227
	v_rcp_f32_e32 v228, v228
	v_rcp_f32_e32 v229, v229
	v_rcp_f32_e32 v230, v230
	v_rcp_f32_e32 v231, v231
	v_pk_mul_f32 v[102:103], v[102:103], v[224:225]
	v_pk_mul_f32 v[104:105], v[104:105], v[226:227]
	v_pk_mul_f32 v[98:99], v[98:99], v[228:229]
	v_pk_mul_f32 v[100:101], v[100:101], v[230:231]
	v_cvt_pk_bf16_f32 v236, v102, v103
	v_cvt_pk_bf16_f32 v237, v104, v105
	v_cvt_pk_bf16_f32 v238, v98, v99
	v_cvt_pk_bf16_f32 v239, v100, v101
	global_store_dwordx4 v252, v[236:239], s[96:97]
	s_add_u32 s96, s96, 0x1000
	s_addc_u32 s97, s97, 0
	v_pk_mul_f32 v[224:225], v[94:95], v[220:221]
	v_pk_mul_f32 v[226:227], v[96:97], v[220:221]
	v_pk_mul_f32 v[228:229], v[90:91], v[220:221]
	v_pk_mul_f32 v[230:231], v[92:93], v[220:221]
	v_exp_f32_e32 v224, v224
	v_exp_f32_e32 v225, v225
	v_exp_f32_e32 v226, v226
	v_exp_f32_e32 v227, v227
	v_exp_f32_e32 v228, v228
	v_exp_f32_e32 v229, v229
	v_exp_f32_e32 v230, v230
	v_exp_f32_e32 v231, v231
	v_pk_add_f32 v[224:225], v[224:225], v[222:223]
	v_pk_add_f32 v[226:227], v[226:227], v[222:223]
	v_pk_add_f32 v[228:229], v[228:229], v[222:223]
	v_pk_add_f32 v[230:231], v[230:231], v[222:223]
	v_rcp_f32_e32 v224, v224
	v_rcp_f32_e32 v225, v225
	v_rcp_f32_e32 v226, v226
	v_rcp_f32_e32 v227, v227
	v_rcp_f32_e32 v228, v228
	v_rcp_f32_e32 v229, v229
	v_rcp_f32_e32 v230, v230
	v_rcp_f32_e32 v231, v231
	v_pk_mul_f32 v[94:95], v[94:95], v[224:225]
	v_pk_mul_f32 v[96:97], v[96:97], v[226:227]
	v_pk_mul_f32 v[90:91], v[90:91], v[228:229]
	v_pk_mul_f32 v[92:93], v[92:93], v[230:231]
	v_cvt_pk_bf16_f32 v232, v94, v95
	v_cvt_pk_bf16_f32 v233, v96, v97
	v_cvt_pk_bf16_f32 v234, v90, v91
	v_cvt_pk_bf16_f32 v235, v92, v93
	global_store_dwordx4 v252, v[232:235], s[96:97]
	s_add_u32 s96, s96, 0x1000
	s_addc_u32 s97, s97, 0
	v_pk_mul_f32 v[224:225], v[86:87], v[220:221]
	v_pk_mul_f32 v[226:227], v[88:89], v[220:221]
	v_pk_mul_f32 v[228:229], v[82:83], v[220:221]
	v_pk_mul_f32 v[230:231], v[84:85], v[220:221]
	v_exp_f32_e32 v224, v224
	v_exp_f32_e32 v225, v225
	v_exp_f32_e32 v226, v226
	v_exp_f32_e32 v227, v227
	v_exp_f32_e32 v228, v228
	v_exp_f32_e32 v229, v229
	v_exp_f32_e32 v230, v230
	v_exp_f32_e32 v231, v231
	v_pk_add_f32 v[224:225], v[224:225], v[222:223]
	v_pk_add_f32 v[226:227], v[226:227], v[222:223]
	v_pk_add_f32 v[228:229], v[228:229], v[222:223]
	v_pk_add_f32 v[230:231], v[230:231], v[222:223]
	v_rcp_f32_e32 v224, v224
	v_rcp_f32_e32 v225, v225
	v_rcp_f32_e32 v226, v226
	v_rcp_f32_e32 v227, v227
	v_rcp_f32_e32 v228, v228
	v_rcp_f32_e32 v229, v229
	v_rcp_f32_e32 v230, v230
	v_rcp_f32_e32 v231, v231
	v_pk_mul_f32 v[86:87], v[86:87], v[224:225]
	v_pk_mul_f32 v[88:89], v[88:89], v[226:227]
	v_pk_mul_f32 v[82:83], v[82:83], v[228:229]
	v_pk_mul_f32 v[84:85], v[84:85], v[230:231]
	v_cvt_pk_bf16_f32 v236, v86, v87
	v_cvt_pk_bf16_f32 v237, v88, v89
	v_cvt_pk_bf16_f32 v238, v82, v83
	v_cvt_pk_bf16_f32 v239, v84, v85
	global_store_dwordx4 v252, v[236:239], s[96:97]
	s_add_u32 s96, s96, 0x1000
	s_addc_u32 s97, s97, 0
	v_pk_mul_f32 v[224:225], v[78:79], v[220:221]
	v_pk_mul_f32 v[226:227], v[80:81], v[220:221]
	v_pk_mul_f32 v[228:229], v[74:75], v[220:221]
	v_pk_mul_f32 v[230:231], v[76:77], v[220:221]
	v_exp_f32_e32 v224, v224
	v_exp_f32_e32 v225, v225
	v_exp_f32_e32 v226, v226
	v_exp_f32_e32 v227, v227
	v_exp_f32_e32 v228, v228
	v_exp_f32_e32 v229, v229
	v_exp_f32_e32 v230, v230
	v_exp_f32_e32 v231, v231
	v_pk_add_f32 v[224:225], v[224:225], v[222:223]
	v_pk_add_f32 v[226:227], v[226:227], v[222:223]
	v_pk_add_f32 v[228:229], v[228:229], v[222:223]
	v_pk_add_f32 v[230:231], v[230:231], v[222:223]
	v_rcp_f32_e32 v224, v224
	v_rcp_f32_e32 v225, v225
	v_rcp_f32_e32 v226, v226
	v_rcp_f32_e32 v227, v227
	v_rcp_f32_e32 v228, v228
	v_rcp_f32_e32 v229, v229
	v_rcp_f32_e32 v230, v230
	v_rcp_f32_e32 v231, v231
	v_pk_mul_f32 v[78:79], v[78:79], v[224:225]
	v_pk_mul_f32 v[80:81], v[80:81], v[226:227]
	v_pk_mul_f32 v[74:75], v[74:75], v[228:229]
	v_pk_mul_f32 v[76:77], v[76:77], v[230:231]
	v_cvt_pk_bf16_f32 v232, v78, v79
	v_cvt_pk_bf16_f32 v233, v80, v81
	v_cvt_pk_bf16_f32 v234, v74, v75
	v_cvt_pk_bf16_f32 v235, v76, v77
	global_store_dwordx4 v252, v[232:235], s[96:97]
	s_add_u32 s96, s96, 0x1000
	s_addc_u32 s97, s97, 0
	v_pk_mul_f32 v[224:225], v[70:71], v[220:221]
	v_pk_mul_f32 v[226:227], v[72:73], v[220:221]
	v_pk_mul_f32 v[228:229], v[66:67], v[220:221]
	v_pk_mul_f32 v[230:231], v[68:69], v[220:221]
	v_exp_f32_e32 v224, v224
	v_exp_f32_e32 v225, v225
	v_exp_f32_e32 v226, v226
	v_exp_f32_e32 v227, v227
	v_exp_f32_e32 v228, v228
	v_exp_f32_e32 v229, v229
	v_exp_f32_e32 v230, v230
	v_exp_f32_e32 v231, v231
	v_pk_add_f32 v[224:225], v[224:225], v[222:223]
	v_pk_add_f32 v[226:227], v[226:227], v[222:223]
	v_pk_add_f32 v[228:229], v[228:229], v[222:223]
	v_pk_add_f32 v[230:231], v[230:231], v[222:223]
	v_rcp_f32_e32 v224, v224
	v_rcp_f32_e32 v225, v225
	v_rcp_f32_e32 v226, v226
	v_rcp_f32_e32 v227, v227
	v_rcp_f32_e32 v228, v228
	v_rcp_f32_e32 v229, v229
	v_rcp_f32_e32 v230, v230
	v_rcp_f32_e32 v231, v231
	v_pk_mul_f32 v[70:71], v[70:71], v[224:225]
	v_pk_mul_f32 v[72:73], v[72:73], v[226:227]
	v_pk_mul_f32 v[66:67], v[66:67], v[228:229]
	v_pk_mul_f32 v[68:69], v[68:69], v[230:231]
; __device__ __forceinline__ unsigned cvt_pk_bf16(float lo, float hi) { unsigned r; asm volatile("v_cvt_pk_bf16_f32 %0, %1, %2" : "=v"(r) : "v"(lo), "v"(hi)); return r; }
; __device__ __forceinline__ float silu_f(float x) { return x * __builtin_amdgcn_rcpf(1.0f + __builtin_amdgcn_exp2f(-x * LOG2E)); }
;     __device__ __forceinline__ void operator()(const f32x4 (&acc)[2][2][4][2], const pg8::Unit& u, int wr, int wc, int fr, int fq, const LAS float* tab) const {
;     ...
;                 for (int bj = 0; bj < 2; ++bj) {
;                     f32x4 v0 = acc[ai][bj][m][0], v1 = acc[ai][bj][m][1];
;                     if (kind == 1) {
; #pragma unroll
;                         for (int e = 0; e < 4; ++e) { v0[e] = silu_f(v0[e]); v1[e] = silu_f(v1[e]); }
;                     } else if (kind == 2) { v0 = v0 * QSCALE; v1 = v1 * QSCALE; }
;                     else if (kind == 3) {
; #pragma unroll
;                         for (int e = 0; e < 4; ++e) { s1 += v0[e] + v1[e]; s2 += v0[e] * v0[e] + v1[e] * v1[e]; }
;                     } else if (kind == 4) {
;                         v0 = v0 * f2; v1 = v1 * f2;
; #pragma unroll
;                         for (int e = 0; e < 4; ++e) s2 += v0[e] * v0[e] + v1[e] * v1[e];
;                     }
;                     u32x4 w; w.x = cvt_pk_bf16(v0[0], v0[1]); w.y = cvt_pk_bf16(v0[2], v0[3]); w.z = cvt_pk_bf16(v1[0], v1[1]); w.w = cvt_pk_bf16(v1[2], v1[3]);
;                     *(u32x4*)(rowp + bj * bjstep) = w;
	v_cvt_pk_bf16_f32 v236, v70, v71
	v_cvt_pk_bf16_f32 v237, v72, v73
	v_cvt_pk_bf16_f32 v238, v66, v67
	v_cvt_pk_bf16_f32 v239, v68, v69
	global_store_dwordx4 v252, v[236:239], s[96:97]
	s_add_u32 s96, s96, 0x1000
	s_addc_u32 s97, s97, 0
	s_add_u32 s96, s96, 0x8000
	s_addc_u32 s97, s97, 0
	v_pk_mul_f32 v[224:225], v[62:63], v[220:221]
	v_pk_mul_f32 v[226:227], v[64:65], v[220:221]
	v_pk_mul_f32 v[228:229], v[58:59], v[220:221]
	v_pk_mul_f32 v[230:231], v[60:61], v[220:221]
	v_exp_f32_e32 v224, v224
	v_exp_f32_e32 v225, v225
	v_exp_f32_e32 v226, v226
	v_exp_f32_e32 v227, v227
	v_exp_f32_e32 v228, v228
	v_exp_f32_e32 v229, v229
	v_exp_f32_e32 v230, v230
	v_exp_f32_e32 v231, v231
	v_pk_add_f32 v[224:225], v[224:225], v[222:223]
	v_pk_add_f32 v[226:227], v[226:227], v[222:223]
	v_pk_add_f32 v[228:229], v[228:229], v[222:223]
	v_pk_add_f32 v[230:231], v[230:231], v[222:223]
	v_rcp_f32_e32 v224, v224
	v_rcp_f32_e32 v225, v225
	v_rcp_f32_e32 v226, v226
	v_rcp_f32_e32 v227, v227
	v_rcp_f32_e32 v228, v228
	v_rcp_f32_e32 v229, v229
	v_rcp_f32_e32 v230, v230
	v_rcp_f32_e32 v231, v231
	v_pk_mul_f32 v[62:63], v[62:63], v[224:225]
	v_pk_mul_f32 v[64:65], v[64:65], v[226:227]
	v_pk_mul_f32 v[58:59], v[58:59], v[228:229]
	v_pk_mul_f32 v[60:61], v[60:61], v[230:231]
	v_cvt_pk_bf16_f32 v232, v62, v63
	v_cvt_pk_bf16_f32 v233, v64, v65
	v_cvt_pk_bf16_f32 v234, v58, v59
	v_cvt_pk_bf16_f32 v235, v60, v61
	global_store_dwordx4 v252, v[232:235], s[96:97]
	s_add_u32 s96, s96, 0x1000
	s_addc_u32 s97, s97, 0
	v_pk_mul_f32 v[224:225], v[54:55], v[220:221]
	v_pk_mul_f32 v[226:227], v[56:57], v[220:221]
	v_pk_mul_f32 v[228:229], v[50:51], v[220:221]
	v_pk_mul_f32 v[230:231], v[52:53], v[220:221]
	v_exp_f32_e32 v224, v224
	v_exp_f32_e32 v225, v225
	v_exp_f32_e32 v226, v226
	v_exp_f32_e32 v227, v227
	v_exp_f32_e32 v228, v228
	v_exp_f32_e32 v229, v229
	v_exp_f32_e32 v230, v230
	v_exp_f32_e32 v231, v231
	v_pk_add_f32 v[224:225], v[224:225], v[222:223]
	v_pk_add_f32 v[226:227], v[226:227], v[222:223]
	v_pk_add_f32 v[228:229], v[228:229], v[222:223]
	v_pk_add_f32 v[230:231], v[230:231], v[222:223]
	v_rcp_f32_e32 v224, v224
	v_rcp_f32_e32 v225, v225
	v_rcp_f32_e32 v226, v226
	v_rcp_f32_e32 v227, v227
	v_rcp_f32_e32 v228, v228
	v_rcp_f32_e32 v229, v229
	v_rcp_f32_e32 v230, v230
	v_rcp_f32_e32 v231, v231
	v_pk_mul_f32 v[54:55], v[54:55], v[224:225]
	v_pk_mul_f32 v[56:57], v[56:57], v[226:227]
	v_pk_mul_f32 v[50:51], v[50:51], v[228:229]
	v_pk_mul_f32 v[52:53], v[52:53], v[230:231]
	v_cvt_pk_bf16_f32 v236, v54, v55
	v_cvt_pk_bf16_f32 v237, v56, v57
	v_cvt_pk_bf16_f32 v238, v50, v51
	v_cvt_pk_bf16_f32 v239, v52, v53
	global_store_dwordx4 v252, v[236:239], s[96:97]
	s_add_u32 s96, s96, 0x1000
	s_addc_u32 s97, s97, 0
	v_pk_mul_f32 v[224:225], v[46:47], v[220:221]
	v_pk_mul_f32 v[226:227], v[48:49], v[220:221]
	v_pk_mul_f32 v[228:229], v[42:43], v[220:221]
	v_pk_mul_f32 v[230:231], v[44:45], v[220:221]
	v_exp_f32_e32 v224, v224
	v_exp_f32_e32 v225, v225
	v_exp_f32_e32 v226, v226
	v_exp_f32_e32 v227, v227
	v_exp_f32_e32 v228, v228
	v_exp_f32_e32 v229, v229
	v_exp_f32_e32 v230, v230
	v_exp_f32_e32 v231, v231
	v_pk_add_f32 v[224:225], v[224:225], v[222:223]
	v_pk_add_f32 v[226:227], v[226:227], v[222:223]
	v_pk_add_f32 v[228:229], v[228:229], v[222:223]
	v_pk_add_f32 v[230:231], v[230:231], v[222:223]
	v_rcp_f32_e32 v224, v224
	v_rcp_f32_e32 v225, v225
	v_rcp_f32_e32 v226, v226
	v_rcp_f32_e32 v227, v227
	v_rcp_f32_e32 v228, v228
	v_rcp_f32_e32 v229, v229
	v_rcp_f32_e32 v230, v230
	v_rcp_f32_e32 v231, v231
	v_pk_mul_f32 v[46:47], v[46:47], v[224:225]
	v_pk_mul_f32 v[48:49], v[48:49], v[226:227]
	v_pk_mul_f32 v[42:43], v[42:43], v[228:229]
	v_pk_mul_f32 v[44:45], v[44:45], v[230:231]
	v_cvt_pk_bf16_f32 v232, v46, v47
	v_cvt_pk_bf16_f32 v233, v48, v49
	v_cvt_pk_bf16_f32 v234, v42, v43
	v_cvt_pk_bf16_f32 v235, v44, v45
	global_store_dwordx4 v252, v[232:235], s[96:97]
	s_add_u32 s96, s96, 0x1000
	s_addc_u32 s97, s97, 0
	v_pk_mul_f32 v[224:225], v[38:39], v[220:221]
	v_pk_mul_f32 v[226:227], v[40:41], v[220:221]
	v_pk_mul_f32 v[228:229], v[34:35], v[220:221]
	v_pk_mul_f32 v[230:231], v[36:37], v[220:221]
	v_exp_f32_e32 v224, v224
	v_exp_f32_e32 v225, v225
	v_exp_f32_e32 v226, v226
	v_exp_f32_e32 v227, v227
	v_exp_f32_e32 v228, v228
	v_exp_f32_e32 v229, v229
	v_exp_f32_e32 v230, v230
	v_exp_f32_e32 v231, v231
	v_pk_add_f32 v[224:225], v[224:225], v[222:223]
	v_pk_add_f32 v[226:227], v[226:227], v[222:223]
	v_pk_add_f32 v[228:229], v[228:229], v[222:223]
	v_pk_add_f32 v[230:231], v[230:231], v[222:223]
	v_rcp_f32_e32 v224, v224
	v_rcp_f32_e32 v225, v225
	v_rcp_f32_e32 v226, v226
	v_rcp_f32_e32 v227, v227
	v_rcp_f32_e32 v228, v228
	v_rcp_f32_e32 v229, v229
	v_rcp_f32_e32 v230, v230
	v_rcp_f32_e32 v231, v231
	v_pk_mul_f32 v[38:39], v[38:39], v[224:225]
	v_pk_mul_f32 v[40:41], v[40:41], v[226:227]
	v_pk_mul_f32 v[34:35], v[34:35], v[228:229]
	v_pk_mul_f32 v[36:37], v[36:37], v[230:231]
	v_cvt_pk_bf16_f32 v236, v38, v39
	v_cvt_pk_bf16_f32 v237, v40, v41
	v_cvt_pk_bf16_f32 v238, v34, v35
	v_cvt_pk_bf16_f32 v239, v36, v37
	global_store_dwordx4 v252, v[236:239], s[96:97]
	s_add_u32 s96, s96, 0x1000
	s_addc_u32 s97, s97, 0
	v_pk_mul_f32 v[224:225], v[30:31], v[220:221]
	v_pk_mul_f32 v[226:227], v[32:33], v[220:221]
	v_pk_mul_f32 v[228:229], v[26:27], v[220:221]
	v_pk_mul_f32 v[230:231], v[28:29], v[220:221]
	v_exp_f32_e32 v224, v224
	v_exp_f32_e32 v225, v225
	v_exp_f32_e32 v226, v226
	v_exp_f32_e32 v227, v227
	v_exp_f32_e32 v228, v228
	v_exp_f32_e32 v229, v229
	v_exp_f32_e32 v230, v230
	v_exp_f32_e32 v231, v231
	v_pk_add_f32 v[224:225], v[224:225], v[222:223]
	v_pk_add_f32 v[226:227], v[226:227], v[222:223]
; __device__ __forceinline__ unsigned cvt_pk_bf16(float lo, float hi) { unsigned r; asm volatile("v_cvt_pk_bf16_f32 %0, %1, %2" : "=v"(r) : "v"(lo), "v"(hi)); return r; }
; __device__ __forceinline__ float silu_f(float x) { return x * __builtin_amdgcn_rcpf(1.0f + __builtin_amdgcn_exp2f(-x * LOG2E)); }
;     __device__ __forceinline__ void operator()(const f32x4 (&acc)[2][2][4][2], const pg8::Unit& u, int wr, int wc, int fr, int fq, const LAS float* tab) const {
;     ...
;                 for (int bj = 0; bj < 2; ++bj) {
;                     f32x4 v0 = acc[ai][bj][m][0], v1 = acc[ai][bj][m][1];
;                     if (kind == 1) {
; #pragma unroll
;                         for (int e = 0; e < 4; ++e) { v0[e] = silu_f(v0[e]); v1[e] = silu_f(v1[e]); }
;                     } else if (kind == 2) { v0 = v0 * QSCALE; v1 = v1 * QSCALE; }
;                     else if (kind == 3) {
; #pragma unroll
;                         for (int e = 0; e < 4; ++e) { s1 += v0[e] + v1[e]; s2 += v0[e] * v0[e] + v1[e] * v1[e]; }
;                     } else if (kind == 4) {
;                         v0 = v0 * f2; v1 = v1 * f2;
; #pragma unroll
;                         for (int e = 0; e < 4; ++e) s2 += v0[e] * v0[e] + v1[e] * v1[e];
;                     }
;                     u32x4 w; w.x = cvt_pk_bf16(v0[0], v0[1]); w.y = cvt_pk_bf16(v0[2], v0[3]); w.z = cvt_pk_bf16(v1[0], v1[1]); w.w = cvt_pk_bf16(v1[2], v1[3]);
;                     *(u32x4*)(rowp + bj * bjstep) = w;
	v_pk_add_f32 v[228:229], v[228:229], v[222:223]
	v_pk_add_f32 v[230:231], v[230:231], v[222:223]
	v_rcp_f32_e32 v224, v224
	v_rcp_f32_e32 v225, v225
	v_rcp_f32_e32 v226, v226
	v_rcp_f32_e32 v227, v227
	v_rcp_f32_e32 v228, v228
	v_rcp_f32_e32 v229, v229
	v_rcp_f32_e32 v230, v230
	v_rcp_f32_e32 v231, v231
	v_pk_mul_f32 v[30:31], v[30:31], v[224:225]
	v_pk_mul_f32 v[32:33], v[32:33], v[226:227]
	v_pk_mul_f32 v[26:27], v[26:27], v[228:229]
	v_pk_mul_f32 v[28:29], v[28:29], v[230:231]
	v_cvt_pk_bf16_f32 v232, v30, v31
	v_cvt_pk_bf16_f32 v233, v32, v33
	v_cvt_pk_bf16_f32 v234, v26, v27
	v_cvt_pk_bf16_f32 v235, v28, v29
	global_store_dwordx4 v252, v[232:235], s[96:97]
	s_add_u32 s96, s96, 0x1000
	s_addc_u32 s97, s97, 0
	v_pk_mul_f32 v[224:225], v[22:23], v[220:221]
	v_pk_mul_f32 v[226:227], v[24:25], v[220:221]
	v_pk_mul_f32 v[228:229], v[18:19], v[220:221]
	v_pk_mul_f32 v[230:231], v[20:21], v[220:221]
	v_exp_f32_e32 v224, v224
	v_exp_f32_e32 v225, v225
	v_exp_f32_e32 v226, v226
	v_exp_f32_e32 v227, v227
	v_exp_f32_e32 v228, v228
	v_exp_f32_e32 v229, v229
	v_exp_f32_e32 v230, v230
	v_exp_f32_e32 v231, v231
	v_pk_add_f32 v[224:225], v[224:225], v[222:223]
	v_pk_add_f32 v[226:227], v[226:227], v[222:223]
	v_pk_add_f32 v[228:229], v[228:229], v[222:223]
	v_pk_add_f32 v[230:231], v[230:231], v[222:223]
	v_rcp_f32_e32 v224, v224
	v_rcp_f32_e32 v225, v225
	v_rcp_f32_e32 v226, v226
	v_rcp_f32_e32 v227, v227
	v_rcp_f32_e32 v228, v228
	v_rcp_f32_e32 v229, v229
	v_rcp_f32_e32 v230, v230
	v_rcp_f32_e32 v231, v231
	v_pk_mul_f32 v[22:23], v[22:23], v[224:225]
	v_pk_mul_f32 v[24:25], v[24:25], v[226:227]
	v_pk_mul_f32 v[18:19], v[18:19], v[228:229]
	v_pk_mul_f32 v[20:21], v[20:21], v[230:231]
	v_cvt_pk_bf16_f32 v236, v22, v23
	v_cvt_pk_bf16_f32 v237, v24, v25
	v_cvt_pk_bf16_f32 v238, v18, v19
	v_cvt_pk_bf16_f32 v239, v20, v21
	global_store_dwordx4 v252, v[236:239], s[96:97]
	s_add_u32 s96, s96, 0x1000
	s_addc_u32 s97, s97, 0
	v_pk_mul_f32 v[224:225], v[14:15], v[220:221]
	v_pk_mul_f32 v[226:227], v[16:17], v[220:221]
	v_pk_mul_f32 v[228:229], v[10:11], v[220:221]
	v_pk_mul_f32 v[230:231], v[12:13], v[220:221]
	v_exp_f32_e32 v224, v224
	v_exp_f32_e32 v225, v225
	v_exp_f32_e32 v226, v226
	v_exp_f32_e32 v227, v227
	v_exp_f32_e32 v228, v228
	v_exp_f32_e32 v229, v229
	v_exp_f32_e32 v230, v230
	v_exp_f32_e32 v231, v231
	v_pk_add_f32 v[224:225], v[224:225], v[222:223]
	v_pk_add_f32 v[226:227], v[226:227], v[222:223]
	v_pk_add_f32 v[228:229], v[228:229], v[222:223]
	v_pk_add_f32 v[230:231], v[230:231], v[222:223]
	v_rcp_f32_e32 v224, v224
	v_rcp_f32_e32 v225, v225
	v_rcp_f32_e32 v226, v226
	v_rcp_f32_e32 v227, v227
	v_rcp_f32_e32 v228, v228
	v_rcp_f32_e32 v229, v229
	v_rcp_f32_e32 v230, v230
	v_rcp_f32_e32 v231, v231
	v_pk_mul_f32 v[14:15], v[14:15], v[224:225]
	v_pk_mul_f32 v[16:17], v[16:17], v[226:227]
	v_pk_mul_f32 v[10:11], v[10:11], v[228:229]
	v_pk_mul_f32 v[12:13], v[12:13], v[230:231]
	v_cvt_pk_bf16_f32 v232, v14, v15
	v_cvt_pk_bf16_f32 v233, v16, v17
	v_cvt_pk_bf16_f32 v234, v10, v11
	v_cvt_pk_bf16_f32 v235, v12, v13
	global_store_dwordx4 v252, v[232:235], s[96:97]
	s_add_u32 s96, s96, 0x1000
	s_addc_u32 s97, s97, 0
	v_pk_mul_f32 v[224:225], v[6:7], v[220:221]
	v_pk_mul_f32 v[226:227], v[8:9], v[220:221]
	v_pk_mul_f32 v[228:229], v[2:3], v[220:221]
	v_pk_mul_f32 v[230:231], v[4:5], v[220:221]
	v_exp_f32_e32 v224, v224
	v_exp_f32_e32 v225, v225
	v_exp_f32_e32 v226, v226
	v_exp_f32_e32 v227, v227
	v_exp_f32_e32 v228, v228
	v_exp_f32_e32 v229, v229
	v_exp_f32_e32 v230, v230
	v_exp_f32_e32 v231, v231
	v_pk_add_f32 v[224:225], v[224:225], v[222:223]
	v_pk_add_f32 v[226:227], v[226:227], v[222:223]
	v_pk_add_f32 v[228:229], v[228:229], v[222:223]
	v_pk_add_f32 v[230:231], v[230:231], v[222:223]
	v_rcp_f32_e32 v224, v224
	v_rcp_f32_e32 v225, v225
	v_rcp_f32_e32 v226, v226
	v_rcp_f32_e32 v227, v227
	v_rcp_f32_e32 v228, v228
	v_rcp_f32_e32 v229, v229
	v_rcp_f32_e32 v230, v230
	v_rcp_f32_e32 v231, v231
	v_pk_mul_f32 v[6:7], v[6:7], v[224:225]
	v_pk_mul_f32 v[8:9], v[8:9], v[226:227]
	v_pk_mul_f32 v[2:3], v[2:3], v[228:229]
	v_pk_mul_f32 v[4:5], v[4:5], v[230:231]
	v_cvt_pk_bf16_f32 v236, v6, v7
	v_cvt_pk_bf16_f32 v237, v8, v9
	v_cvt_pk_bf16_f32 v238, v2, v3
	v_cvt_pk_bf16_f32 v239, v4, v5
	global_store_dwordx4 v252, v[236:239], s[96:97]
	s_add_u32 s96, s96, 0x1000
	s_addc_u32 s97, s97, 0
	s_branch .LBB0_391
; __device__ __forceinline__ unsigned cvt_pk_bf16(float lo, float hi) { unsigned r; asm volatile("v_cvt_pk_bf16_f32 %0, %1, %2" : "=v"(r) : "v"(lo), "v"(hi)); return r; }
; __device__ __forceinline__ float silu_f(float x) { return x * __builtin_amdgcn_rcpf(1.0f + __builtin_amdgcn_exp2f(-x * LOG2E)); }
;     __device__ __forceinline__ void operator()(const f32x4 (&acc)[2][2][4][2], const pg8::Unit& u, int wr, int wc, int fr, int fq, const LAS float* tab) const {
;     ...
;                 for (int bj = 0; bj < 2; ++bj) {
;                     f32x4 v0 = acc[ai][bj][m][0], v1 = acc[ai][bj][m][1];
;                     if (kind == 1) {
; #pragma unroll
;                         for (int e = 0; e < 4; ++e) { v0[e] = silu_f(v0[e]); v1[e] = silu_f(v1[e]); }
;                     } else if (kind == 2) { v0 = v0 * QSCALE; v1 = v1 * QSCALE; }
;                     else if (kind == 3) {
; #pragma unroll
;                         for (int e = 0; e < 4; ++e) { s1 += v0[e] + v1[e]; s2 += v0[e] * v0[e] + v1[e] * v1[e]; }
;                     } else if (kind == 4) {
;                         v0 = v0 * f2; v1 = v1 * f2;
; #pragma unroll
;                         for (int e = 0; e < 4; ++e) s2 += v0[e] * v0[e] + v1[e] * v1[e];
;                     }
;                     u32x4 w; w.x = cvt_pk_bf16(v0[0], v0[1]); w.y = cvt_pk_bf16(v0[2], v0[3]); w.z = cvt_pk_bf16(v1[0], v1[1]); w.w = cvt_pk_bf16(v1[2], v1[3]);
;                     *(u32x4*)(rowp + bj * bjstep) = w;
.Lepi_scale:
	v_pk_mul_f32 v[126:127], v[126:127], s[14:15] op_sel_hi:[1,0]
	v_pk_mul_f32 v[128:129], v[128:129], s[14:15] op_sel_hi:[1,0]
	v_pk_mul_f32 v[122:123], v[122:123], s[14:15] op_sel_hi:[1,0]
	v_pk_mul_f32 v[124:125], v[124:125], s[14:15] op_sel_hi:[1,0]
	v_cvt_pk_bf16_f32 v232, v126, v127
	v_cvt_pk_bf16_f32 v233, v128, v129
	v_cvt_pk_bf16_f32 v234, v122, v123
	v_cvt_pk_bf16_f32 v235, v124, v125
	global_store_dwordx4 v252, v[232:235], s[96:97]
	s_add_u32 s96, s96, 0x1000
	s_addc_u32 s97, s97, 0
	v_pk_mul_f32 v[118:119], v[118:119], s[14:15] op_sel_hi:[1,0]
	v_pk_mul_f32 v[120:121], v[120:121], s[14:15] op_sel_hi:[1,0]
	v_pk_mul_f32 v[114:115], v[114:115], s[14:15] op_sel_hi:[1,0]
	v_pk_mul_f32 v[116:117], v[116:117], s[14:15] op_sel_hi:[1,0]
	v_cvt_pk_bf16_f32 v236, v118, v119
	v_cvt_pk_bf16_f32 v237, v120, v121
	v_cvt_pk_bf16_f32 v238, v114, v115
	v_cvt_pk_bf16_f32 v239, v116, v117
	global_store_dwordx4 v252, v[236:239], s[96:97]
	s_add_u32 s96, s96, 0x1000
	s_addc_u32 s97, s97, 0
	v_pk_mul_f32 v[110:111], v[110:111], s[14:15] op_sel_hi:[1,0]
	v_pk_mul_f32 v[112:113], v[112:113], s[14:15] op_sel_hi:[1,0]
	v_pk_mul_f32 v[106:107], v[106:107], s[14:15] op_sel_hi:[1,0]
	v_pk_mul_f32 v[108:109], v[108:109], s[14:15] op_sel_hi:[1,0]
	v_cvt_pk_bf16_f32 v232, v110, v111
	v_cvt_pk_bf16_f32 v233, v112, v113
	v_cvt_pk_bf16_f32 v234, v106, v107
	v_cvt_pk_bf16_f32 v235, v108, v109
	global_store_dwordx4 v252, v[232:235], s[96:97]
	s_add_u32 s96, s96, 0x1000
	s_addc_u32 s97, s97, 0
	v_pk_mul_f32 v[102:103], v[102:103], s[14:15] op_sel_hi:[1,0]
	v_pk_mul_f32 v[104:105], v[104:105], s[14:15] op_sel_hi:[1,0]
	v_pk_mul_f32 v[98:99], v[98:99], s[14:15] op_sel_hi:[1,0]
	v_pk_mul_f32 v[100:101], v[100:101], s[14:15] op_sel_hi:[1,0]
	v_cvt_pk_bf16_f32 v236, v102, v103
	v_cvt_pk_bf16_f32 v237, v104, v105
	v_cvt_pk_bf16_f32 v238, v98, v99
	v_cvt_pk_bf16_f32 v239, v100, v101
	global_store_dwordx4 v252, v[236:239], s[96:97]
	s_add_u32 s96, s96, 0x1000
	s_addc_u32 s97, s97, 0
	v_pk_mul_f32 v[94:95], v[94:95], s[14:15] op_sel_hi:[1,0]
	v_pk_mul_f32 v[96:97], v[96:97], s[14:15] op_sel_hi:[1,0]
	v_pk_mul_f32 v[90:91], v[90:91], s[14:15] op_sel_hi:[1,0]
	v_pk_mul_f32 v[92:93], v[92:93], s[14:15] op_sel_hi:[1,0]
	v_cvt_pk_bf16_f32 v232, v94, v95
	v_cvt_pk_bf16_f32 v233, v96, v97
	v_cvt_pk_bf16_f32 v234, v90, v91
	v_cvt_pk_bf16_f32 v235, v92, v93
	global_store_dwordx4 v252, v[232:235], s[96:97]
	s_add_u32 s96, s96, 0x1000
	s_addc_u32 s97, s97, 0
	v_pk_mul_f32 v[86:87], v[86:87], s[14:15] op_sel_hi:[1,0]
	v_pk_mul_f32 v[88:89], v[88:89], s[14:15] op_sel_hi:[1,0]
	v_pk_mul_f32 v[82:83], v[82:83], s[14:15] op_sel_hi:[1,0]
	v_pk_mul_f32 v[84:85], v[84:85], s[14:15] op_sel_hi:[1,0]
	v_cvt_pk_bf16_f32 v236, v86, v87
	v_cvt_pk_bf16_f32 v237, v88, v89
	v_cvt_pk_bf16_f32 v238, v82, v83
	v_cvt_pk_bf16_f32 v239, v84, v85
	global_store_dwordx4 v252, v[236:239], s[96:97]
	s_add_u32 s96, s96, 0x1000
	s_addc_u32 s97, s97, 0
	v_pk_mul_f32 v[78:79], v[78:79], s[14:15] op_sel_hi:[1,0]
	v_pk_mul_f32 v[80:81], v[80:81], s[14:15] op_sel_hi:[1,0]
	v_pk_mul_f32 v[74:75], v[74:75], s[14:15] op_sel_hi:[1,0]
	v_pk_mul_f32 v[76:77], v[76:77], s[14:15] op_sel_hi:[1,0]
	v_cvt_pk_bf16_f32 v232, v78, v79
	v_cvt_pk_bf16_f32 v233, v80, v81
	v_cvt_pk_bf16_f32 v234, v74, v75
	v_cvt_pk_bf16_f32 v235, v76, v77
	global_store_dwordx4 v252, v[232:235], s[96:97]
	s_add_u32 s96, s96, 0x1000
	s_addc_u32 s97, s97, 0
	v_pk_mul_f32 v[70:71], v[70:71], s[14:15] op_sel_hi:[1,0]
	v_pk_mul_f32 v[72:73], v[72:73], s[14:15] op_sel_hi:[1,0]
	v_pk_mul_f32 v[66:67], v[66:67], s[14:15] op_sel_hi:[1,0]
	v_pk_mul_f32 v[68:69], v[68:69], s[14:15] op_sel_hi:[1,0]
	v_cvt_pk_bf16_f32 v236, v70, v71
	v_cvt_pk_bf16_f32 v237, v72, v73
	v_cvt_pk_bf16_f32 v238, v66, v67
	v_cvt_pk_bf16_f32 v239, v68, v69
	global_store_dwordx4 v252, v[236:239], s[96:97]
	s_add_u32 s96, s96, 0x1000
	s_addc_u32 s97, s97, 0
	s_add_u32 s96, s96, 0x8000
	s_addc_u32 s97, s97, 0
	v_pk_mul_f32 v[62:63], v[62:63], s[14:15] op_sel_hi:[1,0]
	v_pk_mul_f32 v[64:65], v[64:65], s[14:15] op_sel_hi:[1,0]
	v_pk_mul_f32 v[58:59], v[58:59], s[14:15] op_sel_hi:[1,0]
	v_pk_mul_f32 v[60:61], v[60:61], s[14:15] op_sel_hi:[1,0]
	v_cvt_pk_bf16_f32 v232, v62, v63
	v_cvt_pk_bf16_f32 v233, v64, v65
	v_cvt_pk_bf16_f32 v234, v58, v59
	v_cvt_pk_bf16_f32 v235, v60, v61
	global_store_dwordx4 v252, v[232:235], s[96:97]
	s_add_u32 s96, s96, 0x1000
	s_addc_u32 s97, s97, 0
	v_pk_mul_f32 v[54:55], v[54:55], s[14:15] op_sel_hi:[1,0]
	v_pk_mul_f32 v[56:57], v[56:57], s[14:15] op_sel_hi:[1,0]
	v_pk_mul_f32 v[50:51], v[50:51], s[14:15] op_sel_hi:[1,0]
	v_pk_mul_f32 v[52:53], v[52:53], s[14:15] op_sel_hi:[1,0]
	v_cvt_pk_bf16_f32 v236, v54, v55
	v_cvt_pk_bf16_f32 v237, v56, v57
	v_cvt_pk_bf16_f32 v238, v50, v51
	v_cvt_pk_bf16_f32 v239, v52, v53
	global_store_dwordx4 v252, v[236:239], s[96:97]
	s_add_u32 s96, s96, 0x1000
	s_addc_u32 s97, s97, 0
	v_pk_mul_f32 v[46:47], v[46:47], s[14:15] op_sel_hi:[1,0]
	v_pk_mul_f32 v[48:49], v[48:49], s[14:15] op_sel_hi:[1,0]
	v_pk_mul_f32 v[42:43], v[42:43], s[14:15] op_sel_hi:[1,0]
	v_pk_mul_f32 v[44:45], v[44:45], s[14:15] op_sel_hi:[1,0]
	v_cvt_pk_bf16_f32 v232, v46, v47
	v_cvt_pk_bf16_f32 v233, v48, v49
	v_cvt_pk_bf16_f32 v234, v42, v43
	v_cvt_pk_bf16_f32 v235, v44, v45
	global_store_dwordx4 v252, v[232:235], s[96:97]
	s_add_u32 s96, s96, 0x1000
	s_addc_u32 s97, s97, 0
	v_pk_mul_f32 v[38:39], v[38:39], s[14:15] op_sel_hi:[1,0]
	v_pk_mul_f32 v[40:41], v[40:41], s[14:15] op_sel_hi:[1,0]
	v_pk_mul_f32 v[34:35], v[34:35], s[14:15] op_sel_hi:[1,0]
	v_pk_mul_f32 v[36:37], v[36:37], s[14:15] op_sel_hi:[1,0]
	v_cvt_pk_bf16_f32 v236, v38, v39
; __device__ __forceinline__ unsigned cvt_pk_bf16(float lo, float hi) { unsigned r; asm volatile("v_cvt_pk_bf16_f32 %0, %1, %2" : "=v"(r) : "v"(lo), "v"(hi)); return r; }
; __device__ __forceinline__ float silu_f(float x) { return x * __builtin_amdgcn_rcpf(1.0f + __builtin_amdgcn_exp2f(-x * LOG2E)); }
;     __device__ __forceinline__ void operator()(const f32x4 (&acc)[2][2][4][2], const pg8::Unit& u, int wr, int wc, int fr, int fq, const LAS float* tab) const {
;     ...
;                 for (int bj = 0; bj < 2; ++bj) {
;                     f32x4 v0 = acc[ai][bj][m][0], v1 = acc[ai][bj][m][1];
;                     if (kind == 1) {
; #pragma unroll
;                         for (int e = 0; e < 4; ++e) { v0[e] = silu_f(v0[e]); v1[e] = silu_f(v1[e]); }
;                     } else if (kind == 2) { v0 = v0 * QSCALE; v1 = v1 * QSCALE; }
;                     else if (kind == 3) {
; #pragma unroll
;                         for (int e = 0; e < 4; ++e) { s1 += v0[e] + v1[e]; s2 += v0[e] * v0[e] + v1[e] * v1[e]; }
;                     } else if (kind == 4) {
;                         v0 = v0 * f2; v1 = v1 * f2;
; #pragma unroll
;                         for (int e = 0; e < 4; ++e) s2 += v0[e] * v0[e] + v1[e] * v1[e];
;                     }
;                     u32x4 w; w.x = cvt_pk_bf16(v0[0], v0[1]); w.y = cvt_pk_bf16(v0[2], v0[3]); w.z = cvt_pk_bf16(v1[0], v1[1]); w.w = cvt_pk_bf16(v1[2], v1[3]);
;                     *(u32x4*)(rowp + bj * bjstep) = w;
;                 }
;                 if (kind == 3) {
;                     s1 += __shfl_xor(s1, 16); s1 += __shfl_xor(s1, 32); s2 += __shfl_xor(s2, 16); s2 += __shfl_xor(s2, 32);
;                     if (fq == 0) { float* p = aux + (size_t)row * 32 + ((pn - 12) * 4 + wc) * 2; p[0] = s1; p[1] = s2; }
;                 } else if (kind == 4) {
;                     s2 += __shfl_xor(s2, 16); s2 += __shfl_xor(s2, 32);
;                     if (fq == 0) aux[(size_t)row * 32 + pn * 4 + wc] = s2;
	v_cvt_pk_bf16_f32 v237, v40, v41
	v_cvt_pk_bf16_f32 v238, v34, v35
	v_cvt_pk_bf16_f32 v239, v36, v37
	global_store_dwordx4 v252, v[236:239], s[96:97]
	s_add_u32 s96, s96, 0x1000
	s_addc_u32 s97, s97, 0
	v_pk_mul_f32 v[30:31], v[30:31], s[14:15] op_sel_hi:[1,0]
	v_pk_mul_f32 v[32:33], v[32:33], s[14:15] op_sel_hi:[1,0]
	v_pk_mul_f32 v[26:27], v[26:27], s[14:15] op_sel_hi:[1,0]
	v_pk_mul_f32 v[28:29], v[28:29], s[14:15] op_sel_hi:[1,0]
	v_cvt_pk_bf16_f32 v232, v30, v31
	v_cvt_pk_bf16_f32 v233, v32, v33
	v_cvt_pk_bf16_f32 v234, v26, v27
	v_cvt_pk_bf16_f32 v235, v28, v29
	global_store_dwordx4 v252, v[232:235], s[96:97]
	s_add_u32 s96, s96, 0x1000
	s_addc_u32 s97, s97, 0
	v_pk_mul_f32 v[22:23], v[22:23], s[14:15] op_sel_hi:[1,0]
	v_pk_mul_f32 v[24:25], v[24:25], s[14:15] op_sel_hi:[1,0]
	v_pk_mul_f32 v[18:19], v[18:19], s[14:15] op_sel_hi:[1,0]
	v_pk_mul_f32 v[20:21], v[20:21], s[14:15] op_sel_hi:[1,0]
	v_cvt_pk_bf16_f32 v236, v22, v23
	v_cvt_pk_bf16_f32 v237, v24, v25
	v_cvt_pk_bf16_f32 v238, v18, v19
	v_cvt_pk_bf16_f32 v239, v20, v21
	global_store_dwordx4 v252, v[236:239], s[96:97]
	s_add_u32 s96, s96, 0x1000
	s_addc_u32 s97, s97, 0
	v_pk_mul_f32 v[14:15], v[14:15], s[14:15] op_sel_hi:[1,0]
	v_pk_mul_f32 v[16:17], v[16:17], s[14:15] op_sel_hi:[1,0]
	v_pk_mul_f32 v[10:11], v[10:11], s[14:15] op_sel_hi:[1,0]
	v_pk_mul_f32 v[12:13], v[12:13], s[14:15] op_sel_hi:[1,0]
	v_cvt_pk_bf16_f32 v232, v14, v15
	v_cvt_pk_bf16_f32 v233, v16, v17
	v_cvt_pk_bf16_f32 v234, v10, v11
	v_cvt_pk_bf16_f32 v235, v12, v13
	global_store_dwordx4 v252, v[232:235], s[96:97]
	s_add_u32 s96, s96, 0x1000
	s_addc_u32 s97, s97, 0
	v_pk_mul_f32 v[6:7], v[6:7], s[14:15] op_sel_hi:[1,0]
	v_pk_mul_f32 v[8:9], v[8:9], s[14:15] op_sel_hi:[1,0]
	v_pk_mul_f32 v[2:3], v[2:3], s[14:15] op_sel_hi:[1,0]
	v_pk_mul_f32 v[4:5], v[4:5], s[14:15] op_sel_hi:[1,0]
	v_cvt_pk_bf16_f32 v236, v6, v7
	v_cvt_pk_bf16_f32 v237, v8, v9
	v_cvt_pk_bf16_f32 v238, v2, v3
	v_cvt_pk_bf16_f32 v239, v4, v5
	global_store_dwordx4 v252, v[236:239], s[96:97]
	s_add_u32 s96, s96, 0x1000
	s_addc_u32 s97, s97, 0
	s_branch .LBB0_391
.Lepi_stats:
	s_lshl_b32 s94, s46, 8
	s_lshr_b32 s95, s33, 2
	s_lshl_b32 s95, s95, 6
	s_add_i32 s94, s94, s95
	s_lshl_b32 s94, s94, 7
	s_sub_i32 s95, s4, 12
	s_lshl_b32 s95, s95, 2
	s_add_i32 s95, s95, s93
	s_lshl_b32 s95, s95, 3
	s_add_u32 s94, s94, s95
	s_add_u32 s98, s54, s94
	s_addc_u32 s99, s55, 0
	v_mov_b32_e32 v240, v126
	v_mov_b32_e32 v241, v127
	v_pk_mul_f32 v[242:243], v[126:127], v[126:127]
	v_pk_add_f32 v[240:241], v[240:241], v[128:129]
	v_pk_fma_f32 v[242:243], v[128:129], v[128:129], v[242:243]
	v_pk_add_f32 v[240:241], v[240:241], v[122:123]
	v_pk_fma_f32 v[242:243], v[122:123], v[122:123], v[242:243]
	v_pk_add_f32 v[240:241], v[240:241], v[124:125]
	v_pk_fma_f32 v[242:243], v[124:125], v[124:125], v[242:243]
	v_pk_add_f32 v[240:241], v[240:241], v[118:119]
	v_pk_fma_f32 v[242:243], v[118:119], v[118:119], v[242:243]
	v_pk_add_f32 v[240:241], v[240:241], v[120:121]
	v_pk_fma_f32 v[242:243], v[120:121], v[120:121], v[242:243]
	v_pk_add_f32 v[240:241], v[240:241], v[114:115]
	v_pk_fma_f32 v[242:243], v[114:115], v[114:115], v[242:243]
	v_pk_add_f32 v[240:241], v[240:241], v[116:117]
	v_pk_fma_f32 v[242:243], v[116:117], v[116:117], v[242:243]
	v_add_f32_e32 v240, v240, v241
	v_add_f32_e32 v241, v242, v243
	v_mov_b32_e32 v242, v240
	v_mov_b32_e32 v243, v241
	s_nop 1
	v_permlane16_swap_b32_e32 v242, v240
	v_permlane16_swap_b32_e32 v243, v241
	v_pk_add_f32 v[240:241], v[240:241], v[242:243]
	v_mov_b32_e32 v242, v240
	v_mov_b32_e32 v243, v241
	s_nop 1
	v_permlane32_swap_b32_e32 v242, v240
	v_permlane32_swap_b32_e32 v243, v241
	v_pk_add_f32 v[244:245], v[240:241], v[242:243]
	v_cvt_pk_bf16_f32 v232, v126, v127
	v_cvt_pk_bf16_f32 v233, v128, v129
	v_cvt_pk_bf16_f32 v234, v122, v123
	v_cvt_pk_bf16_f32 v235, v124, v125
	global_store_dwordx4 v252, v[232:235], s[96:97]
	s_add_u32 s96, s96, 0x1000
	s_addc_u32 s97, s97, 0
	v_cvt_pk_bf16_f32 v236, v118, v119
	v_cvt_pk_bf16_f32 v237, v120, v121
	v_cvt_pk_bf16_f32 v238, v114, v115
	v_cvt_pk_bf16_f32 v239, v116, v117
	global_store_dwordx4 v252, v[236:239], s[96:97]
	s_add_u32 s96, s96, 0x1000
	s_addc_u32 s97, s97, 0
	s_and_saveexec_b64 vcc, s[0:1]
	global_store_dwordx2 v253, v[244:245], s[98:99]
	s_or_b64 exec, exec, vcc
	s_add_u32 s98, s98, 0x800
	s_addc_u32 s99, s99, 0
	v_mov_b32_e32 v240, v110
	v_mov_b32_e32 v241, v111
	v_pk_mul_f32 v[242:243], v[110:111], v[110:111]
	v_pk_add_f32 v[240:241], v[240:241], v[112:113]
	v_pk_fma_f32 v[242:243], v[112:113], v[112:113], v[242:243]
	v_pk_add_f32 v[240:241], v[240:241], v[106:107]
	v_pk_fma_f32 v[242:243], v[106:107], v[106:107], v[242:243]
	v_pk_add_f32 v[240:241], v[240:241], v[108:109]
	v_pk_fma_f32 v[242:243], v[108:109], v[108:109], v[242:243]
	v_pk_add_f32 v[240:241], v[240:241], v[102:103]
	v_pk_fma_f32 v[242:243], v[102:103], v[102:103], v[242:243]
	v_pk_add_f32 v[240:241], v[240:241], v[104:105]
	v_pk_fma_f32 v[242:243], v[104:105], v[104:105], v[242:243]
	v_pk_add_f32 v[240:241], v[240:241], v[98:99]
	v_pk_fma_f32 v[242:243], v[98:99], v[98:99], v[242:243]
	v_pk_add_f32 v[240:241], v[240:241], v[100:101]
	v_pk_fma_f32 v[242:243], v[100:101], v[100:101], v[242:243]
	v_add_f32_e32 v240, v240, v241
	v_add_f32_e32 v241, v242, v243
	v_mov_b32_e32 v242, v240
	v_mov_b32_e32 v243, v241
	s_nop 1
	v_permlane16_swap_b32_e32 v242, v240
	v_permlane16_swap_b32_e32 v243, v241
	v_pk_add_f32 v[240:241], v[240:241], v[242:243]
	v_mov_b32_e32 v242, v240
	v_mov_b32_e32 v243, v241
	s_nop 1
	v_permlane32_swap_b32_e32 v242, v240
	v_permlane32_swap_b32_e32 v243, v241
	v_pk_add_f32 v[244:245], v[240:241], v[242:243]
; __device__ __forceinline__ unsigned cvt_pk_bf16(float lo, float hi) { unsigned r; asm volatile("v_cvt_pk_bf16_f32 %0, %1, %2" : "=v"(r) : "v"(lo), "v"(hi)); return r; }
; __device__ __forceinline__ float silu_f(float x) { return x * __builtin_amdgcn_rcpf(1.0f + __builtin_amdgcn_exp2f(-x * LOG2E)); }
;     __device__ __forceinline__ void operator()(const f32x4 (&acc)[2][2][4][2], const pg8::Unit& u, int wr, int wc, int fr, int fq, const LAS float* tab) const {
;     ...
;                 for (int bj = 0; bj < 2; ++bj) {
;                     f32x4 v0 = acc[ai][bj][m][0], v1 = acc[ai][bj][m][1];
;                     if (kind == 1) {
; #pragma unroll
;                         for (int e = 0; e < 4; ++e) { v0[e] = silu_f(v0[e]); v1[e] = silu_f(v1[e]); }
;                     } else if (kind == 2) { v0 = v0 * QSCALE; v1 = v1 * QSCALE; }
;                     else if (kind == 3) {
; #pragma unroll
;                         for (int e = 0; e < 4; ++e) { s1 += v0[e] + v1[e]; s2 += v0[e] * v0[e] + v1[e] * v1[e]; }
;                     } else if (kind == 4) {
;                         v0 = v0 * f2; v1 = v1 * f2;
; #pragma unroll
;                         for (int e = 0; e < 4; ++e) s2 += v0[e] * v0[e] + v1[e] * v1[e];
;                     }
;                     u32x4 w; w.x = cvt_pk_bf16(v0[0], v0[1]); w.y = cvt_pk_bf16(v0[2], v0[3]); w.z = cvt_pk_bf16(v1[0], v1[1]); w.w = cvt_pk_bf16(v1[2], v1[3]);
;                     *(u32x4*)(rowp + bj * bjstep) = w;
;                 }
;                 if (kind == 3) {
;                     s1 += __shfl_xor(s1, 16); s1 += __shfl_xor(s1, 32); s2 += __shfl_xor(s2, 16); s2 += __shfl_xor(s2, 32);
;                     if (fq == 0) { float* p = aux + (size_t)row * 32 + ((pn - 12) * 4 + wc) * 2; p[0] = s1; p[1] = s2; }
	v_cvt_pk_bf16_f32 v232, v110, v111
	v_cvt_pk_bf16_f32 v233, v112, v113
	v_cvt_pk_bf16_f32 v234, v106, v107
	v_cvt_pk_bf16_f32 v235, v108, v109
	global_store_dwordx4 v252, v[232:235], s[96:97]
	s_add_u32 s96, s96, 0x1000
	s_addc_u32 s97, s97, 0
	v_cvt_pk_bf16_f32 v236, v102, v103
	v_cvt_pk_bf16_f32 v237, v104, v105
	v_cvt_pk_bf16_f32 v238, v98, v99
	v_cvt_pk_bf16_f32 v239, v100, v101
	global_store_dwordx4 v252, v[236:239], s[96:97]
	s_add_u32 s96, s96, 0x1000
	s_addc_u32 s97, s97, 0
	s_and_saveexec_b64 vcc, s[0:1]
	global_store_dwordx2 v253, v[244:245], s[98:99]
	s_or_b64 exec, exec, vcc
	s_add_u32 s98, s98, 0x800
	s_addc_u32 s99, s99, 0
	v_mov_b32_e32 v240, v94
	v_mov_b32_e32 v241, v95
	v_pk_mul_f32 v[242:243], v[94:95], v[94:95]
	v_pk_add_f32 v[240:241], v[240:241], v[96:97]
	v_pk_fma_f32 v[242:243], v[96:97], v[96:97], v[242:243]
	v_pk_add_f32 v[240:241], v[240:241], v[90:91]
	v_pk_fma_f32 v[242:243], v[90:91], v[90:91], v[242:243]
	v_pk_add_f32 v[240:241], v[240:241], v[92:93]
	v_pk_fma_f32 v[242:243], v[92:93], v[92:93], v[242:243]
	v_pk_add_f32 v[240:241], v[240:241], v[86:87]
	v_pk_fma_f32 v[242:243], v[86:87], v[86:87], v[242:243]
	v_pk_add_f32 v[240:241], v[240:241], v[88:89]
	v_pk_fma_f32 v[242:243], v[88:89], v[88:89], v[242:243]
	v_pk_add_f32 v[240:241], v[240:241], v[82:83]
	v_pk_fma_f32 v[242:243], v[82:83], v[82:83], v[242:243]
	v_pk_add_f32 v[240:241], v[240:241], v[84:85]
	v_pk_fma_f32 v[242:243], v[84:85], v[84:85], v[242:243]
	v_add_f32_e32 v240, v240, v241
	v_add_f32_e32 v241, v242, v243
	v_mov_b32_e32 v242, v240
	v_mov_b32_e32 v243, v241
	s_nop 1
	v_permlane16_swap_b32_e32 v242, v240
	v_permlane16_swap_b32_e32 v243, v241
	v_pk_add_f32 v[240:241], v[240:241], v[242:243]
	v_mov_b32_e32 v242, v240
	v_mov_b32_e32 v243, v241
	s_nop 1
	v_permlane32_swap_b32_e32 v242, v240
	v_permlane32_swap_b32_e32 v243, v241
	v_pk_add_f32 v[244:245], v[240:241], v[242:243]
	v_cvt_pk_bf16_f32 v232, v94, v95
	v_cvt_pk_bf16_f32 v233, v96, v97
	v_cvt_pk_bf16_f32 v234, v90, v91
	v_cvt_pk_bf16_f32 v235, v92, v93
	global_store_dwordx4 v252, v[232:235], s[96:97]
	s_add_u32 s96, s96, 0x1000
	s_addc_u32 s97, s97, 0
	v_cvt_pk_bf16_f32 v236, v86, v87
	v_cvt_pk_bf16_f32 v237, v88, v89
	v_cvt_pk_bf16_f32 v238, v82, v83
	v_cvt_pk_bf16_f32 v239, v84, v85
	global_store_dwordx4 v252, v[236:239], s[96:97]
	s_add_u32 s96, s96, 0x1000
	s_addc_u32 s97, s97, 0
	s_and_saveexec_b64 vcc, s[0:1]
	global_store_dwordx2 v253, v[244:245], s[98:99]
	s_or_b64 exec, exec, vcc
	s_add_u32 s98, s98, 0x800
	s_addc_u32 s99, s99, 0
	v_mov_b32_e32 v240, v78
	v_mov_b32_e32 v241, v79
	v_pk_mul_f32 v[242:243], v[78:79], v[78:79]
	v_pk_add_f32 v[240:241], v[240:241], v[80:81]
	v_pk_fma_f32 v[242:243], v[80:81], v[80:81], v[242:243]
	v_pk_add_f32 v[240:241], v[240:241], v[74:75]
	v_pk_fma_f32 v[242:243], v[74:75], v[74:75], v[242:243]
	v_pk_add_f32 v[240:241], v[240:241], v[76:77]
	v_pk_fma_f32 v[242:243], v[76:77], v[76:77], v[242:243]
	v_pk_add_f32 v[240:241], v[240:241], v[70:71]
	v_pk_fma_f32 v[242:243], v[70:71], v[70:71], v[242:243]
	v_pk_add_f32 v[240:241], v[240:241], v[72:73]
	v_pk_fma_f32 v[242:243], v[72:73], v[72:73], v[242:243]
	v_pk_add_f32 v[240:241], v[240:241], v[66:67]
	v_pk_fma_f32 v[242:243], v[66:67], v[66:67], v[242:243]
	v_pk_add_f32 v[240:241], v[240:241], v[68:69]
	v_pk_fma_f32 v[242:243], v[68:69], v[68:69], v[242:243]
	v_add_f32_e32 v240, v240, v241
	v_add_f32_e32 v241, v242, v243
	v_mov_b32_e32 v242, v240
	v_mov_b32_e32 v243, v241
	s_nop 1
	v_permlane16_swap_b32_e32 v242, v240
	v_permlane16_swap_b32_e32 v243, v241
	v_pk_add_f32 v[240:241], v[240:241], v[242:243]
	v_mov_b32_e32 v242, v240
	v_mov_b32_e32 v243, v241
	s_nop 1
	v_permlane32_swap_b32_e32 v242, v240
	v_permlane32_swap_b32_e32 v243, v241
	v_pk_add_f32 v[244:245], v[240:241], v[242:243]
	v_cvt_pk_bf16_f32 v232, v78, v79
	v_cvt_pk_bf16_f32 v233, v80, v81
	v_cvt_pk_bf16_f32 v234, v74, v75
	v_cvt_pk_bf16_f32 v235, v76, v77
	global_store_dwordx4 v252, v[232:235], s[96:97]
	s_add_u32 s96, s96, 0x1000
	s_addc_u32 s97, s97, 0
	v_cvt_pk_bf16_f32 v236, v70, v71
	v_cvt_pk_bf16_f32 v237, v72, v73
	v_cvt_pk_bf16_f32 v238, v66, v67
	v_cvt_pk_bf16_f32 v239, v68, v69
	global_store_dwordx4 v252, v[236:239], s[96:97]
	s_add_u32 s96, s96, 0x1000
	s_addc_u32 s97, s97, 0
	s_add_u32 s96, s96, 0x8000
	s_addc_u32 s97, s97, 0
	s_and_saveexec_b64 vcc, s[0:1]
	global_store_dwordx2 v253, v[244:245], s[98:99]
	s_or_b64 exec, exec, vcc
	s_add_u32 s98, s98, 0x2800
	s_addc_u32 s99, s99, 0
	v_mov_b32_e32 v240, v62
	v_mov_b32_e32 v241, v63
	v_pk_mul_f32 v[242:243], v[62:63], v[62:63]
	v_pk_add_f32 v[240:241], v[240:241], v[64:65]
	v_pk_fma_f32 v[242:243], v[64:65], v[64:65], v[242:243]
	v_pk_add_f32 v[240:241], v[240:241], v[58:59]
	v_pk_fma_f32 v[242:243], v[58:59], v[58:59], v[242:243]
	v_pk_add_f32 v[240:241], v[240:241], v[60:61]
	v_pk_fma_f32 v[242:243], v[60:61], v[60:61], v[242:243]
	v_pk_add_f32 v[240:241], v[240:241], v[54:55]
	v_pk_fma_f32 v[242:243], v[54:55], v[54:55], v[242:243]
	v_pk_add_f32 v[240:241], v[240:241], v[56:57]
	v_pk_fma_f32 v[242:243], v[56:57], v[56:57], v[242:243]
	v_pk_add_f32 v[240:241], v[240:241], v[50:51]
	v_pk_fma_f32 v[242:243], v[50:51], v[50:51], v[242:243]
	v_pk_add_f32 v[240:241], v[240:241], v[52:53]
	v_pk_fma_f32 v[242:243], v[52:53], v[52:53], v[242:243]
	v_add_f32_e32 v240, v240, v241
	v_add_f32_e32 v241, v242, v243
	v_mov_b32_e32 v242, v240
	v_mov_b32_e32 v243, v241
	s_nop 1
	v_permlane16_swap_b32_e32 v242, v240
	v_permlane16_swap_b32_e32 v243, v241
	v_pk_add_f32 v[240:241], v[240:241], v[242:243]
	v_mov_b32_e32 v242, v240
	v_mov_b32_e32 v243, v241
	s_nop 1
	v_permlane32_swap_b32_e32 v242, v240
; __device__ __forceinline__ unsigned cvt_pk_bf16(float lo, float hi) { unsigned r; asm volatile("v_cvt_pk_bf16_f32 %0, %1, %2" : "=v"(r) : "v"(lo), "v"(hi)); return r; }
; __device__ __forceinline__ float silu_f(float x) { return x * __builtin_amdgcn_rcpf(1.0f + __builtin_amdgcn_exp2f(-x * LOG2E)); }
;     __device__ __forceinline__ void operator()(const f32x4 (&acc)[2][2][4][2], const pg8::Unit& u, int wr, int wc, int fr, int fq, const LAS float* tab) const {
;     ...
;                 for (int bj = 0; bj < 2; ++bj) {
;                     f32x4 v0 = acc[ai][bj][m][0], v1 = acc[ai][bj][m][1];
;                     if (kind == 1) {
; #pragma unroll
;                         for (int e = 0; e < 4; ++e) { v0[e] = silu_f(v0[e]); v1[e] = silu_f(v1[e]); }
;                     } else if (kind == 2) { v0 = v0 * QSCALE; v1 = v1 * QSCALE; }
;                     else if (kind == 3) {
; #pragma unroll
;                         for (int e = 0; e < 4; ++e) { s1 += v0[e] + v1[e]; s2 += v0[e] * v0[e] + v1[e] * v1[e]; }
;                     } else if (kind == 4) {
;                         v0 = v0 * f2; v1 = v1 * f2;
; #pragma unroll
;                         for (int e = 0; e < 4; ++e) s2 += v0[e] * v0[e] + v1[e] * v1[e];
;                     }
;                     u32x4 w; w.x = cvt_pk_bf16(v0[0], v0[1]); w.y = cvt_pk_bf16(v0[2], v0[3]); w.z = cvt_pk_bf16(v1[0], v1[1]); w.w = cvt_pk_bf16(v1[2], v1[3]);
;                     *(u32x4*)(rowp + bj * bjstep) = w;
;                 }
;                 if (kind == 3) {
;                     s1 += __shfl_xor(s1, 16); s1 += __shfl_xor(s1, 32); s2 += __shfl_xor(s2, 16); s2 += __shfl_xor(s2, 32);
;                     if (fq == 0) { float* p = aux + (size_t)row * 32 + ((pn - 12) * 4 + wc) * 2; p[0] = s1; p[1] = s2; }
	v_permlane32_swap_b32_e32 v243, v241
	v_pk_add_f32 v[244:245], v[240:241], v[242:243]
	v_cvt_pk_bf16_f32 v232, v62, v63
	v_cvt_pk_bf16_f32 v233, v64, v65
	v_cvt_pk_bf16_f32 v234, v58, v59
	v_cvt_pk_bf16_f32 v235, v60, v61
	global_store_dwordx4 v252, v[232:235], s[96:97]
	s_add_u32 s96, s96, 0x1000
	s_addc_u32 s97, s97, 0
	v_cvt_pk_bf16_f32 v236, v54, v55
	v_cvt_pk_bf16_f32 v237, v56, v57
	v_cvt_pk_bf16_f32 v238, v50, v51
	v_cvt_pk_bf16_f32 v239, v52, v53
	global_store_dwordx4 v252, v[236:239], s[96:97]
	s_add_u32 s96, s96, 0x1000
	s_addc_u32 s97, s97, 0
	s_and_saveexec_b64 vcc, s[0:1]
	global_store_dwordx2 v253, v[244:245], s[98:99]
	s_or_b64 exec, exec, vcc
	s_add_u32 s98, s98, 0x800
	s_addc_u32 s99, s99, 0
	v_mov_b32_e32 v240, v46
	v_mov_b32_e32 v241, v47
	v_pk_mul_f32 v[242:243], v[46:47], v[46:47]
	v_pk_add_f32 v[240:241], v[240:241], v[48:49]
	v_pk_fma_f32 v[242:243], v[48:49], v[48:49], v[242:243]
	v_pk_add_f32 v[240:241], v[240:241], v[42:43]
	v_pk_fma_f32 v[242:243], v[42:43], v[42:43], v[242:243]
	v_pk_add_f32 v[240:241], v[240:241], v[44:45]
	v_pk_fma_f32 v[242:243], v[44:45], v[44:45], v[242:243]
	v_pk_add_f32 v[240:241], v[240:241], v[38:39]
	v_pk_fma_f32 v[242:243], v[38:39], v[38:39], v[242:243]
	v_pk_add_f32 v[240:241], v[240:241], v[40:41]
	v_pk_fma_f32 v[242:243], v[40:41], v[40:41], v[242:243]
	v_pk_add_f32 v[240:241], v[240:241], v[34:35]
	v_pk_fma_f32 v[242:243], v[34:35], v[34:35], v[242:243]
	v_pk_add_f32 v[240:241], v[240:241], v[36:37]
	v_pk_fma_f32 v[242:243], v[36:37], v[36:37], v[242:243]
	v_add_f32_e32 v240, v240, v241
	v_add_f32_e32 v241, v242, v243
	v_mov_b32_e32 v242, v240
	v_mov_b32_e32 v243, v241
	s_nop 1
	v_permlane16_swap_b32_e32 v242, v240
	v_permlane16_swap_b32_e32 v243, v241
	v_pk_add_f32 v[240:241], v[240:241], v[242:243]
	v_mov_b32_e32 v242, v240
	v_mov_b32_e32 v243, v241
	s_nop 1
	v_permlane32_swap_b32_e32 v242, v240
	v_permlane32_swap_b32_e32 v243, v241
	v_pk_add_f32 v[244:245], v[240:241], v[242:243]
	v_cvt_pk_bf16_f32 v232, v46, v47
	v_cvt_pk_bf16_f32 v233, v48, v49
	v_cvt_pk_bf16_f32 v234, v42, v43
	v_cvt_pk_bf16_f32 v235, v44, v45
	global_store_dwordx4 v252, v[232:235], s[96:97]
	s_add_u32 s96, s96, 0x1000
	s_addc_u32 s97, s97, 0
	v_cvt_pk_bf16_f32 v236, v38, v39
	v_cvt_pk_bf16_f32 v237, v40, v41
	v_cvt_pk_bf16_f32 v238, v34, v35
	v_cvt_pk_bf16_f32 v239, v36, v37
	global_store_dwordx4 v252, v[236:239], s[96:97]
	s_add_u32 s96, s96, 0x1000
	s_addc_u32 s97, s97, 0
	s_and_saveexec_b64 vcc, s[0:1]
	global_store_dwordx2 v253, v[244:245], s[98:99]
	s_or_b64 exec, exec, vcc
	s_add_u32 s98, s98, 0x800
	s_addc_u32 s99, s99, 0
	v_mov_b32_e32 v240, v30
	v_mov_b32_e32 v241, v31
	v_pk_mul_f32 v[242:243], v[30:31], v[30:31]
	v_pk_add_f32 v[240:241], v[240:241], v[32:33]
	v_pk_fma_f32 v[242:243], v[32:33], v[32:33], v[242:243]
	v_pk_add_f32 v[240:241], v[240:241], v[26:27]
	v_pk_fma_f32 v[242:243], v[26:27], v[26:27], v[242:243]
	v_pk_add_f32 v[240:241], v[240:241], v[28:29]
	v_pk_fma_f32 v[242:243], v[28:29], v[28:29], v[242:243]
	v_pk_add_f32 v[240:241], v[240:241], v[22:23]
	v_pk_fma_f32 v[242:243], v[22:23], v[22:23], v[242:243]
	v_pk_add_f32 v[240:241], v[240:241], v[24:25]
	v_pk_fma_f32 v[242:243], v[24:25], v[24:25], v[242:243]
	v_pk_add_f32 v[240:241], v[240:241], v[18:19]
	v_pk_fma_f32 v[242:243], v[18:19], v[18:19], v[242:243]
	v_pk_add_f32 v[240:241], v[240:241], v[20:21]
	v_pk_fma_f32 v[242:243], v[20:21], v[20:21], v[242:243]
	v_add_f32_e32 v240, v240, v241
	v_add_f32_e32 v241, v242, v243
	v_mov_b32_e32 v242, v240
	v_mov_b32_e32 v243, v241
	s_nop 1
	v_permlane16_swap_b32_e32 v242, v240
	v_permlane16_swap_b32_e32 v243, v241
	v_pk_add_f32 v[240:241], v[240:241], v[242:243]
	v_mov_b32_e32 v242, v240
	v_mov_b32_e32 v243, v241
	s_nop 1
	v_permlane32_swap_b32_e32 v242, v240
	v_permlane32_swap_b32_e32 v243, v241
	v_pk_add_f32 v[244:245], v[240:241], v[242:243]
	v_cvt_pk_bf16_f32 v232, v30, v31
	v_cvt_pk_bf16_f32 v233, v32, v33
	v_cvt_pk_bf16_f32 v234, v26, v27
	v_cvt_pk_bf16_f32 v235, v28, v29
	global_store_dwordx4 v252, v[232:235], s[96:97]
	s_add_u32 s96, s96, 0x1000
	s_addc_u32 s97, s97, 0
	v_cvt_pk_bf16_f32 v236, v22, v23
	v_cvt_pk_bf16_f32 v237, v24, v25
	v_cvt_pk_bf16_f32 v238, v18, v19
	v_cvt_pk_bf16_f32 v239, v20, v21
	global_store_dwordx4 v252, v[236:239], s[96:97]
	s_add_u32 s96, s96, 0x1000
	s_addc_u32 s97, s97, 0
	s_and_saveexec_b64 vcc, s[0:1]
	global_store_dwordx2 v253, v[244:245], s[98:99]
	s_or_b64 exec, exec, vcc
	s_add_u32 s98, s98, 0x800
	s_addc_u32 s99, s99, 0
	v_mov_b32_e32 v240, v14
	v_mov_b32_e32 v241, v15
	v_pk_mul_f32 v[242:243], v[14:15], v[14:15]
	v_pk_add_f32 v[240:241], v[240:241], v[16:17]
	v_pk_fma_f32 v[242:243], v[16:17], v[16:17], v[242:243]
	v_pk_add_f32 v[240:241], v[240:241], v[10:11]
	v_pk_fma_f32 v[242:243], v[10:11], v[10:11], v[242:243]
	v_pk_add_f32 v[240:241], v[240:241], v[12:13]
	v_pk_fma_f32 v[242:243], v[12:13], v[12:13], v[242:243]
	v_pk_add_f32 v[240:241], v[240:241], v[6:7]
	v_pk_fma_f32 v[242:243], v[6:7], v[6:7], v[242:243]
	v_pk_add_f32 v[240:241], v[240:241], v[8:9]
	v_pk_fma_f32 v[242:243], v[8:9], v[8:9], v[242:243]
	v_pk_add_f32 v[240:241], v[240:241], v[2:3]
	v_pk_fma_f32 v[242:243], v[2:3], v[2:3], v[242:243]
	v_pk_add_f32 v[240:241], v[240:241], v[4:5]
	v_pk_fma_f32 v[242:243], v[4:5], v[4:5], v[242:243]
	v_add_f32_e32 v240, v240, v241
	v_add_f32_e32 v241, v242, v243
	v_mov_b32_e32 v242, v240
	v_mov_b32_e32 v243, v241
	s_nop 1
	v_permlane16_swap_b32_e32 v242, v240
	v_permlane16_swap_b32_e32 v243, v241
	v_pk_add_f32 v[240:241], v[240:241], v[242:243]
	v_mov_b32_e32 v242, v240
	v_mov_b32_e32 v243, v241
	s_nop 1
	v_permlane32_swap_b32_e32 v242, v240
	v_permlane32_swap_b32_e32 v243, v241
	v_pk_add_f32 v[244:245], v[240:241], v[242:243]
	v_cvt_pk_bf16_f32 v232, v14, v15
	v_cvt_pk_bf16_f32 v233, v16, v17
	v_cvt_pk_bf16_f32 v234, v10, v11
	v_cvt_pk_bf16_f32 v235, v12, v13
	global_store_dwordx4 v252, v[232:235], s[96:97]
	s_add_u32 s96, s96, 0x1000
	s_addc_u32 s97, s97, 0
	v_cvt_pk_bf16_f32 v236, v6, v7
	v_cvt_pk_bf16_f32 v237, v8, v9
	v_cvt_pk_bf16_f32 v238, v2, v3
	v_cvt_pk_bf16_f32 v239, v4, v5
	global_store_dwordx4 v252, v[236:239], s[96:97]
	s_add_u32 s96, s96, 0x1000
	s_addc_u32 s97, s97, 0
	s_and_saveexec_b64 vcc, s[0:1]
	global_store_dwordx2 v253, v[244:245], s[98:99]
	s_or_b64 exec, exec, vcc
	s_add_u32 s98, s98, 0x800
	s_addc_u32 s99, s99, 0
	s_branch .LBB0_391
